# staged epilogue for MLA G1 RAW/SZ tiles (write-through RAW), ph8 rows remapped to teams (+2nd pass for cache rows), ph7->ph8 team sync
# speedup vs baseline: 1.0257x; 1.0065x over previous
G1E_ph2_ST:
	v_and_b32_e32 v223, 31, v0
	v_mul_u32_u24_e32 v220, 0x110, v223
	v_bfe_u32 v223, v0, 5, 1
	v_lshl_add_u32 v220, v223, 4, v220
	v_bfe_u32 v224, v0, 6, 2
	v_mul_u32_u24_e32 v223, 0x2200, v224
	v_add_u32_e32 v220, v220, v223
	v_bfe_u32 v222, v0, 4, 2
	v_mul_u32_u24_e32 v221, 0x110, v222
	v_add_u32_e32 v221, v221, v223
	v_and_b32_e32 v223, 15, v0
	v_lshl_add_u32 v221, v223, 4, v221
	s_lshr_b32 s85, s35, 6
	s_and_b32 s85, s85, 7
	s_lshl_b32 s85, s85, 8
	s_and_b32 s84, s35, 63
	s_mulk_i32 s84, 0xc0
	v_lshrrev_b32_e32 v224, 1, v224
	v_mul_u32_u24_e32 v224, 0x60, v224
	v_add3_u32 v222, v222, v224, s84
	v_lshlrev_b32_e32 v222, 11, v222
	v_lshl_add_u32 v222, v223, 3, v222
	v_bfe_u32 v223, v0, 6, 1
	v_lshl_add_u32 v222, v223, 7, v222
	v_add_u32_e32 v222, s85, v222
	ds_write_b128 v220, v[82:85]
	ds_write_b128 v220, v[86:89] offset:32
	ds_write_b128 v220, v[90:93] offset:64
	ds_write_b128 v220, v[94:97] offset:96
	ds_write_b128 v220, v[66:69] offset:128
	ds_write_b128 v220, v[70:73] offset:160
	ds_write_b128 v220, v[74:77] offset:192
	ds_write_b128 v220, v[78:81] offset:224
	v_mov_b32_e32 v230, v222
	v_add_u32_e32 v231, 0x2000, v222
	v_add_u32_e32 v232, 0x4000, v222
	v_add_u32_e32 v233, 0x6000, v222
	v_add_u32_e32 v234, 0x8000, v222
	v_add_u32_e32 v235, 0xa000, v222
	v_add_u32_e32 v236, 0xc000, v222
	v_add_u32_e32 v237, 0xe000, v222
	s_waitcnt lgkmcnt(0)
	ds_read_b128 v[82:85], v221
	ds_read_b128 v[86:89], v221 offset:1088
	ds_read_b128 v[90:93], v221 offset:2176
	ds_read_b128 v[94:97], v221 offset:3264
	ds_read_b128 v[66:69], v221 offset:4352
	ds_read_b128 v[70:73], v221 offset:5440
	ds_read_b128 v[74:77], v221 offset:6528
	ds_read_b128 v[78:81], v221 offset:7616
	s_waitcnt lgkmcnt(7)
	v_cvt_pk_bf16_f32 v82, v82, v83
	v_cvt_pk_bf16_f32 v83, v84, v85
	global_store_dwordx2 v230, v[82:83], s[82:83] sc1
	s_waitcnt lgkmcnt(6)
	v_cvt_pk_bf16_f32 v86, v86, v87
	v_cvt_pk_bf16_f32 v87, v88, v89
	global_store_dwordx2 v231, v[86:87], s[82:83] sc1
	s_waitcnt lgkmcnt(5)
	v_cvt_pk_bf16_f32 v90, v90, v91
	v_cvt_pk_bf16_f32 v91, v92, v93
	global_store_dwordx2 v232, v[90:91], s[82:83] sc1
	s_waitcnt lgkmcnt(4)
	v_cvt_pk_bf16_f32 v94, v94, v95
	v_cvt_pk_bf16_f32 v95, v96, v97
	global_store_dwordx2 v233, v[94:95], s[82:83] sc1
	s_waitcnt lgkmcnt(3)
	v_cvt_pk_bf16_f32 v66, v66, v67
	v_cvt_pk_bf16_f32 v67, v68, v69
	global_store_dwordx2 v234, v[66:67], s[82:83] sc1
	s_waitcnt lgkmcnt(2)
	v_cvt_pk_bf16_f32 v70, v70, v71
	v_cvt_pk_bf16_f32 v71, v72, v73
	global_store_dwordx2 v235, v[70:71], s[82:83] sc1
	s_waitcnt lgkmcnt(1)
	v_cvt_pk_bf16_f32 v74, v74, v75
	v_cvt_pk_bf16_f32 v75, v76, v77
	global_store_dwordx2 v236, v[74:75], s[82:83] sc1
	s_waitcnt lgkmcnt(0)
	v_cvt_pk_bf16_f32 v78, v78, v79
	v_cvt_pk_bf16_f32 v79, v80, v81
	global_store_dwordx2 v237, v[78:79], s[82:83] sc1
	ds_write_b128 v220, v[50:53]
	ds_write_b128 v220, v[54:57] offset:32
	ds_write_b128 v220, v[58:61] offset:64
	ds_write_b128 v220, v[62:65] offset:96
	ds_write_b128 v220, v[34:37] offset:128
	ds_write_b128 v220, v[38:41] offset:160
	ds_write_b128 v220, v[42:45] offset:192
	ds_write_b128 v220, v[46:49] offset:224
	v_add_u32_e32 v230, 0x10000, v222
	v_add_u32_e32 v231, 0x12000, v222
	v_add_u32_e32 v232, 0x14000, v222
	v_add_u32_e32 v233, 0x16000, v222
	v_add_u32_e32 v234, 0x18000, v222
	v_add_u32_e32 v235, 0x1a000, v222
	v_add_u32_e32 v236, 0x1c000, v222
	v_add_u32_e32 v237, 0x1e000, v222
	s_waitcnt lgkmcnt(0)
	ds_read_b128 v[50:53], v221
	ds_read_b128 v[54:57], v221 offset:1088
	ds_read_b128 v[58:61], v221 offset:2176
	ds_read_b128 v[62:65], v221 offset:3264
	ds_read_b128 v[34:37], v221 offset:4352
	ds_read_b128 v[38:41], v221 offset:5440
	ds_read_b128 v[42:45], v221 offset:6528
	ds_read_b128 v[46:49], v221 offset:7616
	s_waitcnt lgkmcnt(7)
	v_cvt_pk_bf16_f32 v50, v50, v51
	v_cvt_pk_bf16_f32 v51, v52, v53
	global_store_dwordx2 v230, v[50:51], s[82:83] sc1
	s_waitcnt lgkmcnt(6)
	v_cvt_pk_bf16_f32 v54, v54, v55
	v_cvt_pk_bf16_f32 v55, v56, v57
	global_store_dwordx2 v231, v[54:55], s[82:83] sc1
	s_waitcnt lgkmcnt(5)
	v_cvt_pk_bf16_f32 v58, v58, v59
	v_cvt_pk_bf16_f32 v59, v60, v61
	global_store_dwordx2 v232, v[58:59], s[82:83] sc1
	s_waitcnt lgkmcnt(4)
	v_cvt_pk_bf16_f32 v62, v62, v63
	v_cvt_pk_bf16_f32 v63, v64, v65
	global_store_dwordx2 v233, v[62:63], s[82:83] sc1
	s_waitcnt lgkmcnt(3)
	v_cvt_pk_bf16_f32 v34, v34, v35
	v_cvt_pk_bf16_f32 v35, v36, v37
	global_store_dwordx2 v234, v[34:35], s[82:83] sc1
	s_waitcnt lgkmcnt(2)
	v_cvt_pk_bf16_f32 v38, v38, v39
	v_cvt_pk_bf16_f32 v39, v40, v41
	global_store_dwordx2 v235, v[38:39], s[82:83] sc1
	s_waitcnt lgkmcnt(1)
	v_cvt_pk_bf16_f32 v42, v42, v43
	v_cvt_pk_bf16_f32 v43, v44, v45
	global_store_dwordx2 v236, v[42:43], s[82:83] sc1
	s_waitcnt lgkmcnt(0)
	v_cvt_pk_bf16_f32 v46, v46, v47
	v_cvt_pk_bf16_f32 v47, v48, v49
	global_store_dwordx2 v237, v[46:47], s[82:83] sc1
	ds_write_b128 v220, v[18:21]
	ds_write_b128 v220, v[22:25] offset:32
	ds_write_b128 v220, v[26:29] offset:64
	ds_write_b128 v220, v[30:33] offset:96
	ds_write_b128 v220, v[2:5] offset:128
	ds_write_b128 v220, v[6:9] offset:160
	ds_write_b128 v220, v[10:13] offset:192
	ds_write_b128 v220, v[14:17] offset:224
	v_add_u32_e32 v230, 0x20000, v222
	v_add_u32_e32 v231, 0x22000, v222
	v_add_u32_e32 v232, 0x24000, v222
	v_add_u32_e32 v233, 0x26000, v222
	v_add_u32_e32 v234, 0x28000, v222
	v_add_u32_e32 v235, 0x2a000, v222
	v_add_u32_e32 v236, 0x2c000, v222
	v_add_u32_e32 v237, 0x2e000, v222
	s_waitcnt lgkmcnt(0)
	ds_read_b128 v[18:21], v221
	ds_read_b128 v[22:25], v221 offset:1088
	ds_read_b128 v[26:29], v221 offset:2176
	ds_read_b128 v[30:33], v221 offset:3264
	ds_read_b128 v[2:5], v221 offset:4352
	ds_read_b128 v[6:9], v221 offset:5440
	ds_read_b128 v[10:13], v221 offset:6528
	ds_read_b128 v[14:17], v221 offset:7616
	s_waitcnt lgkmcnt(7)
	v_cvt_pk_bf16_f32 v18, v18, v19
	v_cvt_pk_bf16_f32 v19, v20, v21
	global_store_dwordx2 v230, v[18:19], s[82:83] sc1
	s_waitcnt lgkmcnt(6)
	v_cvt_pk_bf16_f32 v22, v22, v23
	v_cvt_pk_bf16_f32 v23, v24, v25
	global_store_dwordx2 v231, v[22:23], s[82:83] sc1
	s_waitcnt lgkmcnt(5)
	v_cvt_pk_bf16_f32 v26, v26, v27
	v_cvt_pk_bf16_f32 v27, v28, v29
	global_store_dwordx2 v232, v[26:27], s[82:83] sc1
	s_waitcnt lgkmcnt(4)
	v_cvt_pk_bf16_f32 v30, v30, v31
	v_cvt_pk_bf16_f32 v31, v32, v33
	global_store_dwordx2 v233, v[30:31], s[82:83] sc1
	s_waitcnt lgkmcnt(3)
	v_cvt_pk_bf16_f32 v2, v2, v3
	v_cvt_pk_bf16_f32 v3, v4, v5
	global_store_dwordx2 v234, v[2:3], s[82:83] sc1
	s_waitcnt lgkmcnt(2)
	v_cvt_pk_bf16_f32 v6, v6, v7
	v_cvt_pk_bf16_f32 v7, v8, v9
	global_store_dwordx2 v235, v[6:7], s[82:83] sc1
	s_waitcnt lgkmcnt(1)
	v_cvt_pk_bf16_f32 v10, v10, v11
	v_cvt_pk_bf16_f32 v11, v12, v13
	global_store_dwordx2 v236, v[10:11], s[82:83] sc1
	s_waitcnt lgkmcnt(0)
	v_cvt_pk_bf16_f32 v14, v14, v15
	v_cvt_pk_bf16_f32 v15, v16, v17
	global_store_dwordx2 v237, v[14:15], s[82:83] sc1
	s_barrier
	s_mov_b64 s[4:5], exec
	s_branch .LBB0_149

.Lgm_ph7_loop:
	s_waitcnt lgkmcnt(1)
	v_mfma_f32_32x32x16_bf16 v[82:97], v[240:243], v[252:255], v[82:97]
	ds_read_b128 v[220:223], v210 offset:0
	s_add_u32 m0, s81, 0x5000
	s_nop 0
	global_load_lds_dwordx4 v202, s[70:71]
	v_mfma_f32_32x32x16_bf16 v[66:81], v[236:239], v[252:255], v[66:81]
	ds_read_b128 v[232:235], v214 offset:0
	s_add_u32 m0, s82, 0x0
	s_nop 0
	global_load_lds_dwordx4 v207, s[72:73]
	v_mfma_f32_32x32x16_bf16 v[50:65], v[240:243], v[248:251], v[50:65]
	ds_read_b128 v[216:219], v210 offset:4096
	s_add_u32 m0, s82, 0x1000
	s_nop 0
	global_load_lds_dwordx4 v206, s[72:73]
	v_mfma_f32_32x32x16_bf16 v[34:49], v[236:239], v[248:251], v[34:49]
	ds_read_b128 v[228:231], v214 offset:4096
	s_add_u32 m0, s82, 0x2000
	s_nop 0
	global_load_lds_dwordx4 v205, s[72:73]
	s_waitcnt lgkmcnt(4)
	v_mfma_f32_32x32x16_bf16 v[18:33], v[240:243], v[244:247], v[18:33]
	ds_read_b128 v[224:227], v214 offset:8192
	v_mfma_f32_32x32x16_bf16 v[2:17], v[236:239], v[244:247], v[2:17]
	s_add_u32 m0, s82, 0x3000
	s_nop 0
	global_load_lds_dwordx4 v204, s[72:73]
	s_waitcnt lgkmcnt(1)
	v_mfma_f32_32x32x16_bf16 v[82:97], v[220:223], v[232:235], v[82:97]
	ds_read_b128 v[240:243], v209 offset:0
	v_mfma_f32_32x32x16_bf16 v[66:81], v[216:219], v[232:235], v[66:81]
	ds_read_b128 v[252:255], v213 offset:0
	v_mfma_f32_32x32x16_bf16 v[50:65], v[220:223], v[228:231], v[50:65]
	ds_read_b128 v[236:239], v209 offset:4096
	v_mfma_f32_32x32x16_bf16 v[34:49], v[216:219], v[228:231], v[34:49]
	ds_read_b128 v[248:251], v213 offset:4096
	s_waitcnt lgkmcnt(4)
	v_mfma_f32_32x32x16_bf16 v[18:33], v[220:223], v[224:227], v[18:33]
	ds_read_b128 v[244:247], v213 offset:8192
	v_mfma_f32_32x32x16_bf16 v[2:17], v[216:219], v[224:227], v[2:17]
	s_waitcnt lgkmcnt(1)
	v_mfma_f32_32x32x16_bf16 v[82:97], v[240:243], v[252:255], v[82:97]
	ds_read_b128 v[220:223], v208 offset:0
	s_add_u32 s83, s79, s78
	s_add_u32 s83, s83, 2
	s_and_b32 s83, s83, 15
	v_mfma_f32_32x32x16_bf16 v[66:81], v[236:239], v[252:255], v[66:81]
	ds_read_b128 v[232:235], v212 offset:0
	s_lshl_b32 s83, s83, 7
	s_add_u32 s70, s66, s83
	v_mfma_f32_32x32x16_bf16 v[50:65], v[240:243], v[248:251], v[50:65]
	ds_read_b128 v[216:219], v208 offset:4096
	s_addc_u32 s71, s67, 0
	s_add_u32 s72, s68, s83
	v_mfma_f32_32x32x16_bf16 v[34:49], v[236:239], v[248:251], v[34:49]
	ds_read_b128 v[228:231], v212 offset:4096
	s_addc_u32 s73, s69, 0
	s_add_u32 s81, s80, 0x0
	s_add_u32 s82, s80, 0xc000
	s_waitcnt lgkmcnt(4)
	v_mfma_f32_32x32x16_bf16 v[18:33], v[240:243], v[244:247], v[18:33]
	ds_read_b128 v[224:227], v212 offset:8192
	v_mfma_f32_32x32x16_bf16 v[2:17], v[236:239], v[244:247], v[2:17]
	s_waitcnt vmcnt(0) lgkmcnt(0)
	s_barrier
	v_mfma_f32_32x32x16_bf16 v[82:97], v[220:223], v[232:235], v[82:97]
	s_add_u32 m0, s81, 0x0
	ds_read_b128 v[240:243], v211 offset:16384
	global_load_lds_dwordx4 v207, s[70:71]
	v_mfma_f32_32x32x16_bf16 v[66:81], v[216:219], v[232:235], v[66:81]
	s_add_u32 m0, s81, 0x1000
	ds_read_b128 v[252:255], v215 offset:24576
	global_load_lds_dwordx4 v206, s[70:71]
	v_mfma_f32_32x32x16_bf16 v[50:65], v[220:223], v[228:231], v[50:65]
	s_add_u32 m0, s81, 0x2000
	ds_read_b128 v[236:239], v211 offset:20480
	global_load_lds_dwordx4 v205, s[70:71]
	v_mfma_f32_32x32x16_bf16 v[34:49], v[216:219], v[228:231], v[34:49]
	s_add_u32 m0, s81, 0x3000
	ds_read_b128 v[248:251], v215 offset:28672
	global_load_lds_dwordx4 v204, s[70:71]
	v_mfma_f32_32x32x16_bf16 v[18:33], v[220:223], v[224:227], v[18:33]
	s_add_u32 m0, s81, 0x4000
	ds_read_b128 v[244:247], v215 offset:32768
	global_load_lds_dwordx4 v203, s[70:71]
	v_mfma_f32_32x32x16_bf16 v[2:17], v[216:219], v[224:227], v[2:17]
	s_waitcnt lgkmcnt(1)
	v_mfma_f32_32x32x16_bf16 v[82:97], v[240:243], v[252:255], v[82:97]
	ds_read_b128 v[220:223], v210 offset:16384
	s_add_u32 m0, s81, 0x5000
	s_nop 0
	global_load_lds_dwordx4 v202, s[70:71]
	v_mfma_f32_32x32x16_bf16 v[66:81], v[236:239], v[252:255], v[66:81]
	ds_read_b128 v[232:235], v214 offset:24576
	s_add_u32 m0, s82, 0x0
	s_nop 0
	global_load_lds_dwordx4 v207, s[72:73]
	v_mfma_f32_32x32x16_bf16 v[50:65], v[240:243], v[248:251], v[50:65]
	ds_read_b128 v[216:219], v210 offset:20480
	s_add_u32 m0, s82, 0x1000
	s_nop 0
	global_load_lds_dwordx4 v206, s[72:73]
	v_mfma_f32_32x32x16_bf16 v[34:49], v[236:239], v[248:251], v[34:49]
	ds_read_b128 v[228:231], v214 offset:28672
	s_add_u32 m0, s82, 0x2000
	s_nop 0
	global_load_lds_dwordx4 v205, s[72:73]
	s_waitcnt lgkmcnt(4)
	v_mfma_f32_32x32x16_bf16 v[18:33], v[240:243], v[244:247], v[18:33]
	ds_read_b128 v[224:227], v214 offset:32768
	v_mfma_f32_32x32x16_bf16 v[2:17], v[236:239], v[244:247], v[2:17]
	s_add_u32 m0, s82, 0x3000
	s_nop 0
	global_load_lds_dwordx4 v204, s[72:73]
	s_waitcnt lgkmcnt(1)
	v_mfma_f32_32x32x16_bf16 v[82:97], v[220:223], v[232:235], v[82:97]
	ds_read_b128 v[240:243], v209 offset:16384
	v_mfma_f32_32x32x16_bf16 v[66:81], v[216:219], v[232:235], v[66:81]
	ds_read_b128 v[252:255], v213 offset:24576
	v_mfma_f32_32x32x16_bf16 v[50:65], v[220:223], v[228:231], v[50:65]
	ds_read_b128 v[236:239], v209 offset:20480
	v_mfma_f32_32x32x16_bf16 v[34:49], v[216:219], v[228:231], v[34:49]
	ds_read_b128 v[248:251], v213 offset:28672
	s_waitcnt lgkmcnt(4)
	v_mfma_f32_32x32x16_bf16 v[18:33], v[220:223], v[224:227], v[18:33]
	ds_read_b128 v[244:247], v213 offset:32768
	v_mfma_f32_32x32x16_bf16 v[2:17], v[216:219], v[224:227], v[2:17]
	s_waitcnt lgkmcnt(1)
	v_mfma_f32_32x32x16_bf16 v[82:97], v[240:243], v[252:255], v[82:97]
	ds_read_b128 v[220:223], v208 offset:16384
	s_add_u32 s83, s79, s78
	s_add_u32 s83, s83, 3
	s_and_b32 s83, s83, 15
	v_mfma_f32_32x32x16_bf16 v[66:81], v[236:239], v[252:255], v[66:81]
	ds_read_b128 v[232:235], v212 offset:24576
	s_lshl_b32 s83, s83, 7
	s_add_u32 s70, s66, s83
	v_mfma_f32_32x32x16_bf16 v[50:65], v[240:243], v[248:251], v[50:65]
	ds_read_b128 v[216:219], v208 offset:20480
	s_addc_u32 s71, s67, 0
	s_add_u32 s72, s68, s83
	v_mfma_f32_32x32x16_bf16 v[34:49], v[236:239], v[248:251], v[34:49]
	ds_read_b128 v[228:231], v212 offset:28672
	s_addc_u32 s73, s69, 0
	s_add_u32 s81, s80, 0x6000
	s_add_u32 s82, s80, 0x10000
	s_waitcnt lgkmcnt(4)
	v_mfma_f32_32x32x16_bf16 v[18:33], v[240:243], v[244:247], v[18:33]
	ds_read_b128 v[224:227], v212 offset:32768
	v_mfma_f32_32x32x16_bf16 v[2:17], v[236:239], v[244:247], v[2:17]
	s_waitcnt vmcnt(0) lgkmcnt(0)
	s_barrier
	v_mfma_f32_32x32x16_bf16 v[82:97], v[220:223], v[232:235], v[82:97]
	s_add_u32 m0, s81, 0x0
	ds_read_b128 v[240:243], v211 offset:0
	global_load_lds_dwordx4 v207, s[70:71]
	v_mfma_f32_32x32x16_bf16 v[66:81], v[216:219], v[232:235], v[66:81]
	s_add_u32 m0, s81, 0x1000
	ds_read_b128 v[252:255], v215 offset:0
	global_load_lds_dwordx4 v206, s[70:71]
	v_mfma_f32_32x32x16_bf16 v[50:65], v[220:223], v[228:231], v[50:65]
	s_add_u32 m0, s81, 0x2000
	ds_read_b128 v[236:239], v211 offset:4096
	global_load_lds_dwordx4 v205, s[70:71]
	v_mfma_f32_32x32x16_bf16 v[34:49], v[216:219], v[228:231], v[34:49]
	s_add_u32 m0, s81, 0x3000
	ds_read_b128 v[248:251], v215 offset:4096
	global_load_lds_dwordx4 v204, s[70:71]
	v_mfma_f32_32x32x16_bf16 v[18:33], v[220:223], v[224:227], v[18:33]
	s_add_u32 m0, s81, 0x4000
	ds_read_b128 v[244:247], v215 offset:8192
	global_load_lds_dwordx4 v203, s[70:71]
	v_mfma_f32_32x32x16_bf16 v[2:17], v[216:219], v[224:227], v[2:17]
	s_add_u32 s78, s78, 2
	s_cmp_lt_u32 s78, 14
	s_cbranch_scc1 .Lgm_ph7_loop
	s_waitcnt lgkmcnt(1)
	v_mfma_f32_32x32x16_bf16 v[82:97], v[240:243], v[252:255], v[82:97]
	ds_read_b128 v[220:223], v210 offset:0
	s_add_u32 m0, s81, 0x5000
	s_nop 0
	global_load_lds_dwordx4 v202, s[70:71]
	v_mfma_f32_32x32x16_bf16 v[66:81], v[236:239], v[252:255], v[66:81]
	ds_read_b128 v[232:235], v214 offset:0
	s_add_u32 m0, s82, 0x0
	s_nop 0
	global_load_lds_dwordx4 v207, s[72:73]
	v_mfma_f32_32x32x16_bf16 v[50:65], v[240:243], v[248:251], v[50:65]
	ds_read_b128 v[216:219], v210 offset:4096
	s_add_u32 m0, s82, 0x1000
	s_nop 0
	global_load_lds_dwordx4 v206, s[72:73]
	v_mfma_f32_32x32x16_bf16 v[34:49], v[236:239], v[248:251], v[34:49]
	ds_read_b128 v[228:231], v214 offset:4096
	s_add_u32 m0, s82, 0x2000
	s_nop 0
	global_load_lds_dwordx4 v205, s[72:73]
	s_waitcnt lgkmcnt(4)
	v_mfma_f32_32x32x16_bf16 v[18:33], v[240:243], v[244:247], v[18:33]
	ds_read_b128 v[224:227], v214 offset:8192
	v_mfma_f32_32x32x16_bf16 v[2:17], v[236:239], v[244:247], v[2:17]
	s_add_u32 m0, s82, 0x3000
	s_nop 0
	global_load_lds_dwordx4 v204, s[72:73]
	s_waitcnt lgkmcnt(1)
	v_mfma_f32_32x32x16_bf16 v[82:97], v[220:223], v[232:235], v[82:97]
	ds_read_b128 v[240:243], v209 offset:0
	v_mfma_f32_32x32x16_bf16 v[66:81], v[216:219], v[232:235], v[66:81]
	ds_read_b128 v[252:255], v213 offset:0
	v_mfma_f32_32x32x16_bf16 v[50:65], v[220:223], v[228:231], v[50:65]
	ds_read_b128 v[236:239], v209 offset:4096
	v_mfma_f32_32x32x16_bf16 v[34:49], v[216:219], v[228:231], v[34:49]
	ds_read_b128 v[248:251], v213 offset:4096
	s_waitcnt lgkmcnt(4)
	v_mfma_f32_32x32x16_bf16 v[18:33], v[220:223], v[224:227], v[18:33]
	ds_read_b128 v[244:247], v213 offset:8192
	v_mfma_f32_32x32x16_bf16 v[2:17], v[216:219], v[224:227], v[2:17]
	s_waitcnt lgkmcnt(1)
	v_mfma_f32_32x32x16_bf16 v[82:97], v[240:243], v[252:255], v[82:97]
	ds_read_b128 v[220:223], v208 offset:0
	v_mfma_f32_32x32x16_bf16 v[66:81], v[236:239], v[252:255], v[66:81]
	ds_read_b128 v[232:235], v212 offset:0
	v_mfma_f32_32x32x16_bf16 v[50:65], v[240:243], v[248:251], v[50:65]
	ds_read_b128 v[216:219], v208 offset:4096
	v_mfma_f32_32x32x16_bf16 v[34:49], v[236:239], v[248:251], v[34:49]
	ds_read_b128 v[228:231], v212 offset:4096
	s_waitcnt lgkmcnt(4)
	v_mfma_f32_32x32x16_bf16 v[18:33], v[240:243], v[244:247], v[18:33]
	ds_read_b128 v[224:227], v212 offset:8192
	v_mfma_f32_32x32x16_bf16 v[2:17], v[236:239], v[244:247], v[2:17]
	s_waitcnt vmcnt(0) lgkmcnt(0)
	s_barrier
	v_mfma_f32_32x32x16_bf16 v[82:97], v[220:223], v[232:235], v[82:97]
	ds_read_b128 v[240:243], v211 offset:16384
	v_mfma_f32_32x32x16_bf16 v[66:81], v[216:219], v[232:235], v[66:81]
	ds_read_b128 v[252:255], v215 offset:24576
	v_mfma_f32_32x32x16_bf16 v[50:65], v[220:223], v[228:231], v[50:65]
	ds_read_b128 v[236:239], v211 offset:20480
	v_mfma_f32_32x32x16_bf16 v[34:49], v[216:219], v[228:231], v[34:49]
	ds_read_b128 v[248:251], v215 offset:28672
	v_mfma_f32_32x32x16_bf16 v[18:33], v[220:223], v[224:227], v[18:33]
	ds_read_b128 v[244:247], v215 offset:32768
	v_mfma_f32_32x32x16_bf16 v[2:17], v[216:219], v[224:227], v[2:17]
	s_waitcnt lgkmcnt(1)
	v_mfma_f32_32x32x16_bf16 v[82:97], v[240:243], v[252:255], v[82:97]
	ds_read_b128 v[220:223], v210 offset:16384
	v_mfma_f32_32x32x16_bf16 v[66:81], v[236:239], v[252:255], v[66:81]
	ds_read_b128 v[232:235], v214 offset:24576
	v_mfma_f32_32x32x16_bf16 v[50:65], v[240:243], v[248:251], v[50:65]
	ds_read_b128 v[216:219], v210 offset:20480
	v_mfma_f32_32x32x16_bf16 v[34:49], v[236:239], v[248:251], v[34:49]
	ds_read_b128 v[228:231], v214 offset:28672
	s_waitcnt lgkmcnt(4)
	v_mfma_f32_32x32x16_bf16 v[18:33], v[240:243], v[244:247], v[18:33]
	ds_read_b128 v[224:227], v214 offset:32768
	v_mfma_f32_32x32x16_bf16 v[2:17], v[236:239], v[244:247], v[2:17]
	s_waitcnt lgkmcnt(1)
	v_mfma_f32_32x32x16_bf16 v[82:97], v[220:223], v[232:235], v[82:97]
	ds_read_b128 v[240:243], v209 offset:16384
	v_mfma_f32_32x32x16_bf16 v[66:81], v[216:219], v[232:235], v[66:81]
	ds_read_b128 v[252:255], v213 offset:24576
	v_mfma_f32_32x32x16_bf16 v[50:65], v[220:223], v[228:231], v[50:65]
	ds_read_b128 v[236:239], v209 offset:20480
	v_mfma_f32_32x32x16_bf16 v[34:49], v[216:219], v[228:231], v[34:49]
	ds_read_b128 v[248:251], v213 offset:28672
	s_waitcnt lgkmcnt(4)
	v_mfma_f32_32x32x16_bf16 v[18:33], v[220:223], v[224:227], v[18:33]
	ds_read_b128 v[244:247], v213 offset:32768
	v_mfma_f32_32x32x16_bf16 v[2:17], v[216:219], v[224:227], v[2:17]
	s_waitcnt lgkmcnt(1)
	v_mfma_f32_32x32x16_bf16 v[82:97], v[240:243], v[252:255], v[82:97]
	ds_read_b128 v[220:223], v208 offset:16384
	v_mfma_f32_32x32x16_bf16 v[66:81], v[236:239], v[252:255], v[66:81]
	ds_read_b128 v[232:235], v212 offset:24576
	v_mfma_f32_32x32x16_bf16 v[50:65], v[240:243], v[248:251], v[50:65]
	ds_read_b128 v[216:219], v208 offset:20480
	v_mfma_f32_32x32x16_bf16 v[34:49], v[236:239], v[248:251], v[34:49]
	ds_read_b128 v[228:231], v212 offset:28672
	s_waitcnt lgkmcnt(4)
	v_mfma_f32_32x32x16_bf16 v[18:33], v[240:243], v[244:247], v[18:33]
	ds_read_b128 v[224:227], v212 offset:32768
	v_mfma_f32_32x32x16_bf16 v[2:17], v[236:239], v[244:247], v[2:17]
	s_waitcnt vmcnt(0) lgkmcnt(0)
	s_barrier
	v_mfma_f32_32x32x16_bf16 v[82:97], v[220:223], v[232:235], v[82:97]
	v_mfma_f32_32x32x16_bf16 v[66:81], v[216:219], v[232:235], v[66:81]
	v_mfma_f32_32x32x16_bf16 v[50:65], v[220:223], v[228:231], v[50:65]
	v_mfma_f32_32x32x16_bf16 v[34:49], v[216:219], v[228:231], v[34:49]
	v_mfma_f32_32x32x16_bf16 v[18:33], v[220:223], v[224:227], v[18:33]
	v_mfma_f32_32x32x16_bf16 v[2:17], v[216:219], v[224:227], v[2:17]
	s_nop 7
	s_nop 7
	s_setprio 0
	s_lshr_b32 s84, s56, 6
	s_cmp_eq_u32 s84, 6
	s_cbranch_scc1 G1E_ph7_ORIG
	s_cmp_eq_u32 s84, 14
	s_cbranch_scc1 G1E_ph7_ORIG
	s_cmp_lt_u32 s84, 6
	s_cbranch_scc1 G1E_ph7_U
	s_load_dwordx2 s[82:83], s[0:1], 0x98
	v_mul_f32_e32 v198, 0xbfb8aa3b, v2
	v_mul_f32_e32 v199, 0xbfb8aa3b, v3
	v_mul_f32_e32 v200, 0xbfb8aa3b, v4
	v_mul_f32_e32 v201, 0xbfb8aa3b, v5
	v_exp_f32_e32 v198, v198
	v_exp_f32_e32 v199, v199
	v_exp_f32_e32 v200, v200
	v_exp_f32_e32 v201, v201
	s_nop 0
	v_add_f32_e32 v198, 1.0, v198
	v_add_f32_e32 v199, 1.0, v199
	v_add_f32_e32 v200, 1.0, v200
	v_add_f32_e32 v201, 1.0, v201
	v_div_scale_f32 v202, s[84:85], v198, v198, v2
	v_div_scale_f32 v203, s[84:85], v199, v199, v3
	v_div_scale_f32 v204, s[84:85], v200, v200, v4
	v_div_scale_f32 v205, s[84:85], v201, v201, v5
	v_rcp_f32_e32 v206, v202
	v_rcp_f32_e32 v207, v203
	v_rcp_f32_e32 v208, v204
	v_rcp_f32_e32 v209, v205
	s_nop 0
	v_div_scale_f32 v210, vcc, v2, v198, v2
	v_fma_f32 v212, -v202, v206, 1.0
	v_fmac_f32_e32 v206, v212, v206
	v_mul_f32_e32 v211, v210, v206
	v_fma_f32 v212, -v202, v211, v210
	v_fmac_f32_e32 v211, v212, v206
	v_fma_f32 v212, -v202, v211, v210
	v_div_fmas_f32 v212, v212, v206, v211
	v_div_fixup_f32 v2, v212, v198, v2
	v_div_scale_f32 v210, vcc, v3, v199, v3
	v_fma_f32 v212, -v203, v207, 1.0
	v_fmac_f32_e32 v207, v212, v207
	v_mul_f32_e32 v211, v210, v207
	v_fma_f32 v212, -v203, v211, v210
	v_fmac_f32_e32 v211, v212, v207
	v_fma_f32 v212, -v203, v211, v210
	v_div_fmas_f32 v212, v212, v207, v211
	v_div_fixup_f32 v3, v212, v199, v3
	v_div_scale_f32 v210, vcc, v4, v200, v4
	v_fma_f32 v212, -v204, v208, 1.0
	v_fmac_f32_e32 v208, v212, v208
	v_mul_f32_e32 v211, v210, v208
	v_fma_f32 v212, -v204, v211, v210
	v_fmac_f32_e32 v211, v212, v208
	v_fma_f32 v212, -v204, v211, v210
	v_div_fmas_f32 v212, v212, v208, v211
	v_div_fixup_f32 v4, v212, v200, v4
	v_div_scale_f32 v210, vcc, v5, v201, v5
	v_fma_f32 v212, -v205, v209, 1.0
	v_fmac_f32_e32 v209, v212, v209
	v_mul_f32_e32 v211, v210, v209
	v_fma_f32 v212, -v205, v211, v210
	v_fmac_f32_e32 v211, v212, v209
	v_fma_f32 v212, -v205, v211, v210
	v_div_fmas_f32 v212, v212, v209, v211
	v_div_fixup_f32 v5, v212, v201, v5
	v_mul_f32_e32 v198, 0xbfb8aa3b, v6
	v_mul_f32_e32 v199, 0xbfb8aa3b, v7
	v_mul_f32_e32 v200, 0xbfb8aa3b, v8
	v_mul_f32_e32 v201, 0xbfb8aa3b, v9
	v_exp_f32_e32 v198, v198
	v_exp_f32_e32 v199, v199
	v_exp_f32_e32 v200, v200
	v_exp_f32_e32 v201, v201
	s_nop 0
	v_add_f32_e32 v198, 1.0, v198
	v_add_f32_e32 v199, 1.0, v199
	v_add_f32_e32 v200, 1.0, v200
	v_add_f32_e32 v201, 1.0, v201
	v_div_scale_f32 v202, s[84:85], v198, v198, v6
	v_div_scale_f32 v203, s[84:85], v199, v199, v7
	v_div_scale_f32 v204, s[84:85], v200, v200, v8
	v_div_scale_f32 v205, s[84:85], v201, v201, v9
	v_rcp_f32_e32 v206, v202
	v_rcp_f32_e32 v207, v203
	v_rcp_f32_e32 v208, v204
	v_rcp_f32_e32 v209, v205
	s_nop 0
	v_div_scale_f32 v210, vcc, v6, v198, v6
	v_fma_f32 v212, -v202, v206, 1.0
	v_fmac_f32_e32 v206, v212, v206
	v_mul_f32_e32 v211, v210, v206
	v_fma_f32 v212, -v202, v211, v210
	v_fmac_f32_e32 v211, v212, v206
	v_fma_f32 v212, -v202, v211, v210
	v_div_fmas_f32 v212, v212, v206, v211
	v_div_fixup_f32 v6, v212, v198, v6
	v_div_scale_f32 v210, vcc, v7, v199, v7
	v_fma_f32 v212, -v203, v207, 1.0
	v_fmac_f32_e32 v207, v212, v207
	v_mul_f32_e32 v211, v210, v207
	v_fma_f32 v212, -v203, v211, v210
	v_fmac_f32_e32 v211, v212, v207
	v_fma_f32 v212, -v203, v211, v210
	v_div_fmas_f32 v212, v212, v207, v211
	v_div_fixup_f32 v7, v212, v199, v7
	v_div_scale_f32 v210, vcc, v8, v200, v8
	v_fma_f32 v212, -v204, v208, 1.0
	v_fmac_f32_e32 v208, v212, v208
	v_mul_f32_e32 v211, v210, v208
	v_fma_f32 v212, -v204, v211, v210
	v_fmac_f32_e32 v211, v212, v208
	v_fma_f32 v212, -v204, v211, v210
	v_div_fmas_f32 v212, v212, v208, v211
	v_div_fixup_f32 v8, v212, v200, v8
	v_div_scale_f32 v210, vcc, v9, v201, v9
	v_fma_f32 v212, -v205, v209, 1.0
	v_fmac_f32_e32 v209, v212, v209
	v_mul_f32_e32 v211, v210, v209
	v_fma_f32 v212, -v205, v211, v210
	v_fmac_f32_e32 v211, v212, v209
	v_fma_f32 v212, -v205, v211, v210
	v_div_fmas_f32 v212, v212, v209, v211
	v_div_fixup_f32 v9, v212, v201, v9
	v_mul_f32_e32 v198, 0xbfb8aa3b, v10
	v_mul_f32_e32 v199, 0xbfb8aa3b, v11
	v_mul_f32_e32 v200, 0xbfb8aa3b, v12
	v_mul_f32_e32 v201, 0xbfb8aa3b, v13
	v_exp_f32_e32 v198, v198
	v_exp_f32_e32 v199, v199
	v_exp_f32_e32 v200, v200
	v_exp_f32_e32 v201, v201
	s_nop 0
	v_add_f32_e32 v198, 1.0, v198
	v_add_f32_e32 v199, 1.0, v199
	v_add_f32_e32 v200, 1.0, v200
	v_add_f32_e32 v201, 1.0, v201
	v_div_scale_f32 v202, s[84:85], v198, v198, v10
	v_div_scale_f32 v203, s[84:85], v199, v199, v11
	v_div_scale_f32 v204, s[84:85], v200, v200, v12
	v_div_scale_f32 v205, s[84:85], v201, v201, v13
	v_rcp_f32_e32 v206, v202
	v_rcp_f32_e32 v207, v203
	v_rcp_f32_e32 v208, v204
	v_rcp_f32_e32 v209, v205
	s_nop 0
	v_div_scale_f32 v210, vcc, v10, v198, v10
	v_fma_f32 v212, -v202, v206, 1.0
	v_fmac_f32_e32 v206, v212, v206
	v_mul_f32_e32 v211, v210, v206
	v_fma_f32 v212, -v202, v211, v210
	v_fmac_f32_e32 v211, v212, v206
	v_fma_f32 v212, -v202, v211, v210
	v_div_fmas_f32 v212, v212, v206, v211
	v_div_fixup_f32 v10, v212, v198, v10
	v_div_scale_f32 v210, vcc, v11, v199, v11
	v_fma_f32 v212, -v203, v207, 1.0
	v_fmac_f32_e32 v207, v212, v207
	v_mul_f32_e32 v211, v210, v207
	v_fma_f32 v212, -v203, v211, v210
	v_fmac_f32_e32 v211, v212, v207
	v_fma_f32 v212, -v203, v211, v210
	v_div_fmas_f32 v212, v212, v207, v211
	v_div_fixup_f32 v11, v212, v199, v11
	v_div_scale_f32 v210, vcc, v12, v200, v12
	v_fma_f32 v212, -v204, v208, 1.0
	v_fmac_f32_e32 v208, v212, v208
	v_mul_f32_e32 v211, v210, v208
	v_fma_f32 v212, -v204, v211, v210
	v_fmac_f32_e32 v211, v212, v208
	v_fma_f32 v212, -v204, v211, v210
	v_div_fmas_f32 v212, v212, v208, v211
	v_div_fixup_f32 v12, v212, v200, v12
	v_div_scale_f32 v210, vcc, v13, v201, v13
	v_fma_f32 v212, -v205, v209, 1.0
	v_fmac_f32_e32 v209, v212, v209
	v_mul_f32_e32 v211, v210, v209
	v_fma_f32 v212, -v205, v211, v210
	v_fmac_f32_e32 v211, v212, v209
	v_fma_f32 v212, -v205, v211, v210
	v_div_fmas_f32 v212, v212, v209, v211
	v_div_fixup_f32 v13, v212, v201, v13
	v_mul_f32_e32 v198, 0xbfb8aa3b, v14
	v_mul_f32_e32 v199, 0xbfb8aa3b, v15
	v_mul_f32_e32 v200, 0xbfb8aa3b, v16
	v_mul_f32_e32 v201, 0xbfb8aa3b, v17
	v_exp_f32_e32 v198, v198
	v_exp_f32_e32 v199, v199
	v_exp_f32_e32 v200, v200
	v_exp_f32_e32 v201, v201
	s_nop 0
	v_add_f32_e32 v198, 1.0, v198
	v_add_f32_e32 v199, 1.0, v199
	v_add_f32_e32 v200, 1.0, v200
	v_add_f32_e32 v201, 1.0, v201
	v_div_scale_f32 v202, s[84:85], v198, v198, v14
	v_div_scale_f32 v203, s[84:85], v199, v199, v15
	v_div_scale_f32 v204, s[84:85], v200, v200, v16
	v_div_scale_f32 v205, s[84:85], v201, v201, v17
	v_rcp_f32_e32 v206, v202
	v_rcp_f32_e32 v207, v203
	v_rcp_f32_e32 v208, v204
	v_rcp_f32_e32 v209, v205
	s_nop 0
	v_div_scale_f32 v210, vcc, v14, v198, v14
	v_fma_f32 v212, -v202, v206, 1.0
	v_fmac_f32_e32 v206, v212, v206
	v_mul_f32_e32 v211, v210, v206
	v_fma_f32 v212, -v202, v211, v210
	v_fmac_f32_e32 v211, v212, v206
	v_fma_f32 v212, -v202, v211, v210
	v_div_fmas_f32 v212, v212, v206, v211
	v_div_fixup_f32 v14, v212, v198, v14
	v_div_scale_f32 v210, vcc, v15, v199, v15
	v_fma_f32 v212, -v203, v207, 1.0
	v_fmac_f32_e32 v207, v212, v207
	v_mul_f32_e32 v211, v210, v207
	v_fma_f32 v212, -v203, v211, v210
	v_fmac_f32_e32 v211, v212, v207
	v_fma_f32 v212, -v203, v211, v210
	v_div_fmas_f32 v212, v212, v207, v211
	v_div_fixup_f32 v15, v212, v199, v15
	v_div_scale_f32 v210, vcc, v16, v200, v16
	v_fma_f32 v212, -v204, v208, 1.0
	v_fmac_f32_e32 v208, v212, v208
	v_mul_f32_e32 v211, v210, v208
	v_fma_f32 v212, -v204, v211, v210
	v_fmac_f32_e32 v211, v212, v208
	v_fma_f32 v212, -v204, v211, v210
	v_div_fmas_f32 v212, v212, v208, v211
	v_div_fixup_f32 v16, v212, v200, v16
	v_div_scale_f32 v210, vcc, v17, v201, v17
	v_fma_f32 v212, -v205, v209, 1.0
	v_fmac_f32_e32 v209, v212, v209
	v_mul_f32_e32 v211, v210, v209
	v_fma_f32 v212, -v205, v211, v210
	v_fmac_f32_e32 v211, v212, v209
	v_fma_f32 v212, -v205, v211, v210
	v_div_fmas_f32 v212, v212, v209, v211
	v_div_fixup_f32 v17, v212, v201, v17
	v_mul_f32_e32 v198, 0xbfb8aa3b, v18
	v_mul_f32_e32 v199, 0xbfb8aa3b, v19
	v_mul_f32_e32 v200, 0xbfb8aa3b, v20
	v_mul_f32_e32 v201, 0xbfb8aa3b, v21
	v_exp_f32_e32 v198, v198
	v_exp_f32_e32 v199, v199
	v_exp_f32_e32 v200, v200
	v_exp_f32_e32 v201, v201
	s_nop 0
	v_add_f32_e32 v198, 1.0, v198
	v_add_f32_e32 v199, 1.0, v199
	v_add_f32_e32 v200, 1.0, v200
	v_add_f32_e32 v201, 1.0, v201
	v_div_scale_f32 v202, s[84:85], v198, v198, v18
	v_div_scale_f32 v203, s[84:85], v199, v199, v19
	v_div_scale_f32 v204, s[84:85], v200, v200, v20
	v_div_scale_f32 v205, s[84:85], v201, v201, v21
	v_rcp_f32_e32 v206, v202
	v_rcp_f32_e32 v207, v203
	v_rcp_f32_e32 v208, v204
	v_rcp_f32_e32 v209, v205
	s_nop 0
	v_div_scale_f32 v210, vcc, v18, v198, v18
	v_fma_f32 v212, -v202, v206, 1.0
	v_fmac_f32_e32 v206, v212, v206
	v_mul_f32_e32 v211, v210, v206
	v_fma_f32 v212, -v202, v211, v210
	v_fmac_f32_e32 v211, v212, v206
	v_fma_f32 v212, -v202, v211, v210
	v_div_fmas_f32 v212, v212, v206, v211
	v_div_fixup_f32 v18, v212, v198, v18
	v_div_scale_f32 v210, vcc, v19, v199, v19
	v_fma_f32 v212, -v203, v207, 1.0
	v_fmac_f32_e32 v207, v212, v207
	v_mul_f32_e32 v211, v210, v207
	v_fma_f32 v212, -v203, v211, v210
	v_fmac_f32_e32 v211, v212, v207
	v_fma_f32 v212, -v203, v211, v210
	v_div_fmas_f32 v212, v212, v207, v211
	v_div_fixup_f32 v19, v212, v199, v19
	v_div_scale_f32 v210, vcc, v20, v200, v20
	v_fma_f32 v212, -v204, v208, 1.0
	v_fmac_f32_e32 v208, v212, v208
	v_mul_f32_e32 v211, v210, v208
	v_fma_f32 v212, -v204, v211, v210
	v_fmac_f32_e32 v211, v212, v208
	v_fma_f32 v212, -v204, v211, v210
	v_div_fmas_f32 v212, v212, v208, v211
	v_div_fixup_f32 v20, v212, v200, v20
	v_div_scale_f32 v210, vcc, v21, v201, v21
	v_fma_f32 v212, -v205, v209, 1.0
	v_fmac_f32_e32 v209, v212, v209
	v_mul_f32_e32 v211, v210, v209
	v_fma_f32 v212, -v205, v211, v210
	v_fmac_f32_e32 v211, v212, v209
	v_fma_f32 v212, -v205, v211, v210
	v_div_fmas_f32 v212, v212, v209, v211
	v_div_fixup_f32 v21, v212, v201, v21
	v_mul_f32_e32 v198, 0xbfb8aa3b, v22
	v_mul_f32_e32 v199, 0xbfb8aa3b, v23
	v_mul_f32_e32 v200, 0xbfb8aa3b, v24
	v_mul_f32_e32 v201, 0xbfb8aa3b, v25
	v_exp_f32_e32 v198, v198
	v_exp_f32_e32 v199, v199
	v_exp_f32_e32 v200, v200
	v_exp_f32_e32 v201, v201
	s_nop 0
	v_add_f32_e32 v198, 1.0, v198
	v_add_f32_e32 v199, 1.0, v199
	v_add_f32_e32 v200, 1.0, v200
	v_add_f32_e32 v201, 1.0, v201
	v_div_scale_f32 v202, s[84:85], v198, v198, v22
	v_div_scale_f32 v203, s[84:85], v199, v199, v23
	v_div_scale_f32 v204, s[84:85], v200, v200, v24
	v_div_scale_f32 v205, s[84:85], v201, v201, v25
	v_rcp_f32_e32 v206, v202
	v_rcp_f32_e32 v207, v203
	v_rcp_f32_e32 v208, v204
	v_rcp_f32_e32 v209, v205
	s_nop 0
	v_div_scale_f32 v210, vcc, v22, v198, v22
	v_fma_f32 v212, -v202, v206, 1.0
	v_fmac_f32_e32 v206, v212, v206
	v_mul_f32_e32 v211, v210, v206
	v_fma_f32 v212, -v202, v211, v210
	v_fmac_f32_e32 v211, v212, v206
	v_fma_f32 v212, -v202, v211, v210
	v_div_fmas_f32 v212, v212, v206, v211
	v_div_fixup_f32 v22, v212, v198, v22
	v_div_scale_f32 v210, vcc, v23, v199, v23
	v_fma_f32 v212, -v203, v207, 1.0
	v_fmac_f32_e32 v207, v212, v207
	v_mul_f32_e32 v211, v210, v207
	v_fma_f32 v212, -v203, v211, v210
	v_fmac_f32_e32 v211, v212, v207
	v_fma_f32 v212, -v203, v211, v210
	v_div_fmas_f32 v212, v212, v207, v211
	v_div_fixup_f32 v23, v212, v199, v23
	v_div_scale_f32 v210, vcc, v24, v200, v24
	v_fma_f32 v212, -v204, v208, 1.0
	v_fmac_f32_e32 v208, v212, v208
	v_mul_f32_e32 v211, v210, v208
	v_fma_f32 v212, -v204, v211, v210
	v_fmac_f32_e32 v211, v212, v208
	v_fma_f32 v212, -v204, v211, v210
	v_div_fmas_f32 v212, v212, v208, v211
	v_div_fixup_f32 v24, v212, v200, v24
	v_div_scale_f32 v210, vcc, v25, v201, v25
	v_fma_f32 v212, -v205, v209, 1.0
	v_fmac_f32_e32 v209, v212, v209
	v_mul_f32_e32 v211, v210, v209
	v_fma_f32 v212, -v205, v211, v210
	v_fmac_f32_e32 v211, v212, v209
	v_fma_f32 v212, -v205, v211, v210
	v_div_fmas_f32 v212, v212, v209, v211
	v_div_fixup_f32 v25, v212, v201, v25
	v_mul_f32_e32 v198, 0xbfb8aa3b, v26
	v_mul_f32_e32 v199, 0xbfb8aa3b, v27
	v_mul_f32_e32 v200, 0xbfb8aa3b, v28
	v_mul_f32_e32 v201, 0xbfb8aa3b, v29
	v_exp_f32_e32 v198, v198
	v_exp_f32_e32 v199, v199
	v_exp_f32_e32 v200, v200
	v_exp_f32_e32 v201, v201
	s_nop 0
	v_add_f32_e32 v198, 1.0, v198
	v_add_f32_e32 v199, 1.0, v199
	v_add_f32_e32 v200, 1.0, v200
	v_add_f32_e32 v201, 1.0, v201
	v_div_scale_f32 v202, s[84:85], v198, v198, v26
	v_div_scale_f32 v203, s[84:85], v199, v199, v27
	v_div_scale_f32 v204, s[84:85], v200, v200, v28
	v_div_scale_f32 v205, s[84:85], v201, v201, v29
	v_rcp_f32_e32 v206, v202
	v_rcp_f32_e32 v207, v203
	v_rcp_f32_e32 v208, v204
	v_rcp_f32_e32 v209, v205
	s_nop 0
	v_div_scale_f32 v210, vcc, v26, v198, v26
	v_fma_f32 v212, -v202, v206, 1.0
	v_fmac_f32_e32 v206, v212, v206
	v_mul_f32_e32 v211, v210, v206
	v_fma_f32 v212, -v202, v211, v210
	v_fmac_f32_e32 v211, v212, v206
	v_fma_f32 v212, -v202, v211, v210
	v_div_fmas_f32 v212, v212, v206, v211
	v_div_fixup_f32 v26, v212, v198, v26
	v_div_scale_f32 v210, vcc, v27, v199, v27
	v_fma_f32 v212, -v203, v207, 1.0
	v_fmac_f32_e32 v207, v212, v207
	v_mul_f32_e32 v211, v210, v207
	v_fma_f32 v212, -v203, v211, v210
	v_fmac_f32_e32 v211, v212, v207
	v_fma_f32 v212, -v203, v211, v210
	v_div_fmas_f32 v212, v212, v207, v211
	v_div_fixup_f32 v27, v212, v199, v27
	v_div_scale_f32 v210, vcc, v28, v200, v28
	v_fma_f32 v212, -v204, v208, 1.0
	v_fmac_f32_e32 v208, v212, v208
	v_mul_f32_e32 v211, v210, v208
	v_fma_f32 v212, -v204, v211, v210
	v_fmac_f32_e32 v211, v212, v208
	v_fma_f32 v212, -v204, v211, v210
	v_div_fmas_f32 v212, v212, v208, v211
	v_div_fixup_f32 v28, v212, v200, v28
	v_div_scale_f32 v210, vcc, v29, v201, v29
	v_fma_f32 v212, -v205, v209, 1.0
	v_fmac_f32_e32 v209, v212, v209
	v_mul_f32_e32 v211, v210, v209
	v_fma_f32 v212, -v205, v211, v210
	v_fmac_f32_e32 v211, v212, v209
	v_fma_f32 v212, -v205, v211, v210
	v_div_fmas_f32 v212, v212, v209, v211
	v_div_fixup_f32 v29, v212, v201, v29
	v_mul_f32_e32 v198, 0xbfb8aa3b, v30
	v_mul_f32_e32 v199, 0xbfb8aa3b, v31
	v_mul_f32_e32 v200, 0xbfb8aa3b, v32
	v_mul_f32_e32 v201, 0xbfb8aa3b, v33
	v_exp_f32_e32 v198, v198
	v_exp_f32_e32 v199, v199
	v_exp_f32_e32 v200, v200
	v_exp_f32_e32 v201, v201
	s_nop 0
	v_add_f32_e32 v198, 1.0, v198
	v_add_f32_e32 v199, 1.0, v199
	v_add_f32_e32 v200, 1.0, v200
	v_add_f32_e32 v201, 1.0, v201
	v_div_scale_f32 v202, s[84:85], v198, v198, v30
	v_div_scale_f32 v203, s[84:85], v199, v199, v31
	v_div_scale_f32 v204, s[84:85], v200, v200, v32
	v_div_scale_f32 v205, s[84:85], v201, v201, v33
	v_rcp_f32_e32 v206, v202
	v_rcp_f32_e32 v207, v203
	v_rcp_f32_e32 v208, v204
	v_rcp_f32_e32 v209, v205
	s_nop 0
	v_div_scale_f32 v210, vcc, v30, v198, v30
	v_fma_f32 v212, -v202, v206, 1.0
	v_fmac_f32_e32 v206, v212, v206
	v_mul_f32_e32 v211, v210, v206
	v_fma_f32 v212, -v202, v211, v210
	v_fmac_f32_e32 v211, v212, v206
	v_fma_f32 v212, -v202, v211, v210
	v_div_fmas_f32 v212, v212, v206, v211
	v_div_fixup_f32 v30, v212, v198, v30
	v_div_scale_f32 v210, vcc, v31, v199, v31
	v_fma_f32 v212, -v203, v207, 1.0
	v_fmac_f32_e32 v207, v212, v207
	v_mul_f32_e32 v211, v210, v207
	v_fma_f32 v212, -v203, v211, v210
	v_fmac_f32_e32 v211, v212, v207
	v_fma_f32 v212, -v203, v211, v210
	v_div_fmas_f32 v212, v212, v207, v211
	v_div_fixup_f32 v31, v212, v199, v31
	v_div_scale_f32 v210, vcc, v32, v200, v32
	v_fma_f32 v212, -v204, v208, 1.0
	v_fmac_f32_e32 v208, v212, v208
	v_mul_f32_e32 v211, v210, v208
	v_fma_f32 v212, -v204, v211, v210
	v_fmac_f32_e32 v211, v212, v208
	v_fma_f32 v212, -v204, v211, v210
	v_div_fmas_f32 v212, v212, v208, v211
	v_div_fixup_f32 v32, v212, v200, v32
	v_div_scale_f32 v210, vcc, v33, v201, v33
	v_fma_f32 v212, -v205, v209, 1.0
	v_fmac_f32_e32 v209, v212, v209
	v_mul_f32_e32 v211, v210, v209
	v_fma_f32 v212, -v205, v211, v210
	v_fmac_f32_e32 v211, v212, v209
	v_fma_f32 v212, -v205, v211, v210
	v_div_fmas_f32 v212, v212, v209, v211
	v_div_fixup_f32 v33, v212, v201, v33
	v_mul_f32_e32 v198, 0xbfb8aa3b, v34
	v_mul_f32_e32 v199, 0xbfb8aa3b, v35
	v_mul_f32_e32 v200, 0xbfb8aa3b, v36
	v_mul_f32_e32 v201, 0xbfb8aa3b, v37
	v_exp_f32_e32 v198, v198
	v_exp_f32_e32 v199, v199
	v_exp_f32_e32 v200, v200
	v_exp_f32_e32 v201, v201
	s_nop 0
	v_add_f32_e32 v198, 1.0, v198
	v_add_f32_e32 v199, 1.0, v199
	v_add_f32_e32 v200, 1.0, v200
	v_add_f32_e32 v201, 1.0, v201
	v_div_scale_f32 v202, s[84:85], v198, v198, v34
	v_div_scale_f32 v203, s[84:85], v199, v199, v35
	v_div_scale_f32 v204, s[84:85], v200, v200, v36
	v_div_scale_f32 v205, s[84:85], v201, v201, v37
	v_rcp_f32_e32 v206, v202
	v_rcp_f32_e32 v207, v203
	v_rcp_f32_e32 v208, v204
	v_rcp_f32_e32 v209, v205
	s_nop 0
	v_div_scale_f32 v210, vcc, v34, v198, v34
	v_fma_f32 v212, -v202, v206, 1.0
	v_fmac_f32_e32 v206, v212, v206
	v_mul_f32_e32 v211, v210, v206
	v_fma_f32 v212, -v202, v211, v210
	v_fmac_f32_e32 v211, v212, v206
	v_fma_f32 v212, -v202, v211, v210
	v_div_fmas_f32 v212, v212, v206, v211
	v_div_fixup_f32 v34, v212, v198, v34
	v_div_scale_f32 v210, vcc, v35, v199, v35
	v_fma_f32 v212, -v203, v207, 1.0
	v_fmac_f32_e32 v207, v212, v207
	v_mul_f32_e32 v211, v210, v207
	v_fma_f32 v212, -v203, v211, v210
	v_fmac_f32_e32 v211, v212, v207
	v_fma_f32 v212, -v203, v211, v210
	v_div_fmas_f32 v212, v212, v207, v211
	v_div_fixup_f32 v35, v212, v199, v35
	v_div_scale_f32 v210, vcc, v36, v200, v36
	v_fma_f32 v212, -v204, v208, 1.0
	v_fmac_f32_e32 v208, v212, v208
	v_mul_f32_e32 v211, v210, v208
	v_fma_f32 v212, -v204, v211, v210
	v_fmac_f32_e32 v211, v212, v208
	v_fma_f32 v212, -v204, v211, v210
	v_div_fmas_f32 v212, v212, v208, v211
	v_div_fixup_f32 v36, v212, v200, v36
	v_div_scale_f32 v210, vcc, v37, v201, v37
	v_fma_f32 v212, -v205, v209, 1.0
	v_fmac_f32_e32 v209, v212, v209
	v_mul_f32_e32 v211, v210, v209
	v_fma_f32 v212, -v205, v211, v210
	v_fmac_f32_e32 v211, v212, v209
	v_fma_f32 v212, -v205, v211, v210
	v_div_fmas_f32 v212, v212, v209, v211
	v_div_fixup_f32 v37, v212, v201, v37
	v_mul_f32_e32 v198, 0xbfb8aa3b, v38
	v_mul_f32_e32 v199, 0xbfb8aa3b, v39
	v_mul_f32_e32 v200, 0xbfb8aa3b, v40
	v_mul_f32_e32 v201, 0xbfb8aa3b, v41
	v_exp_f32_e32 v198, v198
	v_exp_f32_e32 v199, v199
	v_exp_f32_e32 v200, v200
	v_exp_f32_e32 v201, v201
	s_nop 0
	v_add_f32_e32 v198, 1.0, v198
	v_add_f32_e32 v199, 1.0, v199
	v_add_f32_e32 v200, 1.0, v200
	v_add_f32_e32 v201, 1.0, v201
	v_div_scale_f32 v202, s[84:85], v198, v198, v38
	v_div_scale_f32 v203, s[84:85], v199, v199, v39
	v_div_scale_f32 v204, s[84:85], v200, v200, v40
	v_div_scale_f32 v205, s[84:85], v201, v201, v41
	v_rcp_f32_e32 v206, v202
	v_rcp_f32_e32 v207, v203
	v_rcp_f32_e32 v208, v204
	v_rcp_f32_e32 v209, v205
	s_nop 0
	v_div_scale_f32 v210, vcc, v38, v198, v38
	v_fma_f32 v212, -v202, v206, 1.0
	v_fmac_f32_e32 v206, v212, v206
	v_mul_f32_e32 v211, v210, v206
	v_fma_f32 v212, -v202, v211, v210
	v_fmac_f32_e32 v211, v212, v206
	v_fma_f32 v212, -v202, v211, v210
	v_div_fmas_f32 v212, v212, v206, v211
	v_div_fixup_f32 v38, v212, v198, v38
	v_div_scale_f32 v210, vcc, v39, v199, v39
	v_fma_f32 v212, -v203, v207, 1.0
	v_fmac_f32_e32 v207, v212, v207
	v_mul_f32_e32 v211, v210, v207
	v_fma_f32 v212, -v203, v211, v210
	v_fmac_f32_e32 v211, v212, v207
	v_fma_f32 v212, -v203, v211, v210
	v_div_fmas_f32 v212, v212, v207, v211
	v_div_fixup_f32 v39, v212, v199, v39
	v_div_scale_f32 v210, vcc, v40, v200, v40
	v_fma_f32 v212, -v204, v208, 1.0
	v_fmac_f32_e32 v208, v212, v208
	v_mul_f32_e32 v211, v210, v208
	v_fma_f32 v212, -v204, v211, v210
	v_fmac_f32_e32 v211, v212, v208
	v_fma_f32 v212, -v204, v211, v210
	v_div_fmas_f32 v212, v212, v208, v211
	v_div_fixup_f32 v40, v212, v200, v40
	v_div_scale_f32 v210, vcc, v41, v201, v41
	v_fma_f32 v212, -v205, v209, 1.0
	v_fmac_f32_e32 v209, v212, v209
	v_mul_f32_e32 v211, v210, v209
	v_fma_f32 v212, -v205, v211, v210
	v_fmac_f32_e32 v211, v212, v209
	v_fma_f32 v212, -v205, v211, v210
	v_div_fmas_f32 v212, v212, v209, v211
	v_div_fixup_f32 v41, v212, v201, v41
	v_mul_f32_e32 v198, 0xbfb8aa3b, v42
	v_mul_f32_e32 v199, 0xbfb8aa3b, v43
	v_mul_f32_e32 v200, 0xbfb8aa3b, v44
	v_mul_f32_e32 v201, 0xbfb8aa3b, v45
	v_exp_f32_e32 v198, v198
	v_exp_f32_e32 v199, v199
	v_exp_f32_e32 v200, v200
	v_exp_f32_e32 v201, v201
	s_nop 0
	v_add_f32_e32 v198, 1.0, v198
	v_add_f32_e32 v199, 1.0, v199
	v_add_f32_e32 v200, 1.0, v200
	v_add_f32_e32 v201, 1.0, v201
	v_div_scale_f32 v202, s[84:85], v198, v198, v42
	v_div_scale_f32 v203, s[84:85], v199, v199, v43
	v_div_scale_f32 v204, s[84:85], v200, v200, v44
	v_div_scale_f32 v205, s[84:85], v201, v201, v45
	v_rcp_f32_e32 v206, v202
	v_rcp_f32_e32 v207, v203
	v_rcp_f32_e32 v208, v204
	v_rcp_f32_e32 v209, v205
	s_nop 0
	v_div_scale_f32 v210, vcc, v42, v198, v42
	v_fma_f32 v212, -v202, v206, 1.0
	v_fmac_f32_e32 v206, v212, v206
	v_mul_f32_e32 v211, v210, v206
	v_fma_f32 v212, -v202, v211, v210
	v_fmac_f32_e32 v211, v212, v206
	v_fma_f32 v212, -v202, v211, v210
	v_div_fmas_f32 v212, v212, v206, v211
	v_div_fixup_f32 v42, v212, v198, v42
	v_div_scale_f32 v210, vcc, v43, v199, v43
	v_fma_f32 v212, -v203, v207, 1.0
	v_fmac_f32_e32 v207, v212, v207
	v_mul_f32_e32 v211, v210, v207
	v_fma_f32 v212, -v203, v211, v210
	v_fmac_f32_e32 v211, v212, v207
	v_fma_f32 v212, -v203, v211, v210
	v_div_fmas_f32 v212, v212, v207, v211
	v_div_fixup_f32 v43, v212, v199, v43
	v_div_scale_f32 v210, vcc, v44, v200, v44
	v_fma_f32 v212, -v204, v208, 1.0
	v_fmac_f32_e32 v208, v212, v208
	v_mul_f32_e32 v211, v210, v208
	v_fma_f32 v212, -v204, v211, v210
	v_fmac_f32_e32 v211, v212, v208
	v_fma_f32 v212, -v204, v211, v210
	v_div_fmas_f32 v212, v212, v208, v211
	v_div_fixup_f32 v44, v212, v200, v44
	v_div_scale_f32 v210, vcc, v45, v201, v45
	v_fma_f32 v212, -v205, v209, 1.0
	v_fmac_f32_e32 v209, v212, v209
	v_mul_f32_e32 v211, v210, v209
	v_fma_f32 v212, -v205, v211, v210
	v_fmac_f32_e32 v211, v212, v209
	v_fma_f32 v212, -v205, v211, v210
	v_div_fmas_f32 v212, v212, v209, v211
	v_div_fixup_f32 v45, v212, v201, v45
	v_mul_f32_e32 v198, 0xbfb8aa3b, v46
	v_mul_f32_e32 v199, 0xbfb8aa3b, v47
	v_mul_f32_e32 v200, 0xbfb8aa3b, v48
	v_mul_f32_e32 v201, 0xbfb8aa3b, v49
	v_exp_f32_e32 v198, v198
	v_exp_f32_e32 v199, v199
	v_exp_f32_e32 v200, v200
	v_exp_f32_e32 v201, v201
	s_nop 0
	v_add_f32_e32 v198, 1.0, v198
	v_add_f32_e32 v199, 1.0, v199
	v_add_f32_e32 v200, 1.0, v200
	v_add_f32_e32 v201, 1.0, v201
	v_div_scale_f32 v202, s[84:85], v198, v198, v46
	v_div_scale_f32 v203, s[84:85], v199, v199, v47
	v_div_scale_f32 v204, s[84:85], v200, v200, v48
	v_div_scale_f32 v205, s[84:85], v201, v201, v49
	v_rcp_f32_e32 v206, v202
	v_rcp_f32_e32 v207, v203
	v_rcp_f32_e32 v208, v204
	v_rcp_f32_e32 v209, v205
	s_nop 0
	v_div_scale_f32 v210, vcc, v46, v198, v46
	v_fma_f32 v212, -v202, v206, 1.0
	v_fmac_f32_e32 v206, v212, v206
	v_mul_f32_e32 v211, v210, v206
	v_fma_f32 v212, -v202, v211, v210
	v_fmac_f32_e32 v211, v212, v206
	v_fma_f32 v212, -v202, v211, v210
	v_div_fmas_f32 v212, v212, v206, v211
	v_div_fixup_f32 v46, v212, v198, v46
	v_div_scale_f32 v210, vcc, v47, v199, v47
	v_fma_f32 v212, -v203, v207, 1.0
	v_fmac_f32_e32 v207, v212, v207
	v_mul_f32_e32 v211, v210, v207
	v_fma_f32 v212, -v203, v211, v210
	v_fmac_f32_e32 v211, v212, v207
	v_fma_f32 v212, -v203, v211, v210
	v_div_fmas_f32 v212, v212, v207, v211
	v_div_fixup_f32 v47, v212, v199, v47
	v_div_scale_f32 v210, vcc, v48, v200, v48
	v_fma_f32 v212, -v204, v208, 1.0
	v_fmac_f32_e32 v208, v212, v208
	v_mul_f32_e32 v211, v210, v208
	v_fma_f32 v212, -v204, v211, v210
	v_fmac_f32_e32 v211, v212, v208
	v_fma_f32 v212, -v204, v211, v210
	v_div_fmas_f32 v212, v212, v208, v211
	v_div_fixup_f32 v48, v212, v200, v48
	v_div_scale_f32 v210, vcc, v49, v201, v49
	v_fma_f32 v212, -v205, v209, 1.0
	v_fmac_f32_e32 v209, v212, v209
	v_mul_f32_e32 v211, v210, v209
	v_fma_f32 v212, -v205, v211, v210
	v_fmac_f32_e32 v211, v212, v209
	v_fma_f32 v212, -v205, v211, v210
	v_div_fmas_f32 v212, v212, v209, v211
	v_div_fixup_f32 v49, v212, v201, v49
	v_mul_f32_e32 v198, 0xbfb8aa3b, v50
	v_mul_f32_e32 v199, 0xbfb8aa3b, v51
	v_mul_f32_e32 v200, 0xbfb8aa3b, v52
	v_mul_f32_e32 v201, 0xbfb8aa3b, v53
	v_exp_f32_e32 v198, v198
	v_exp_f32_e32 v199, v199
	v_exp_f32_e32 v200, v200
	v_exp_f32_e32 v201, v201
	s_nop 0
	v_add_f32_e32 v198, 1.0, v198
	v_add_f32_e32 v199, 1.0, v199
	v_add_f32_e32 v200, 1.0, v200
	v_add_f32_e32 v201, 1.0, v201
	v_div_scale_f32 v202, s[84:85], v198, v198, v50
	v_div_scale_f32 v203, s[84:85], v199, v199, v51
	v_div_scale_f32 v204, s[84:85], v200, v200, v52
	v_div_scale_f32 v205, s[84:85], v201, v201, v53
	v_rcp_f32_e32 v206, v202
	v_rcp_f32_e32 v207, v203
	v_rcp_f32_e32 v208, v204
	v_rcp_f32_e32 v209, v205
	s_nop 0
	v_div_scale_f32 v210, vcc, v50, v198, v50
	v_fma_f32 v212, -v202, v206, 1.0
	v_fmac_f32_e32 v206, v212, v206
	v_mul_f32_e32 v211, v210, v206
	v_fma_f32 v212, -v202, v211, v210
	v_fmac_f32_e32 v211, v212, v206
	v_fma_f32 v212, -v202, v211, v210
	v_div_fmas_f32 v212, v212, v206, v211
	v_div_fixup_f32 v50, v212, v198, v50
	v_div_scale_f32 v210, vcc, v51, v199, v51
	v_fma_f32 v212, -v203, v207, 1.0
	v_fmac_f32_e32 v207, v212, v207
	v_mul_f32_e32 v211, v210, v207
	v_fma_f32 v212, -v203, v211, v210
	v_fmac_f32_e32 v211, v212, v207
	v_fma_f32 v212, -v203, v211, v210
	v_div_fmas_f32 v212, v212, v207, v211
	v_div_fixup_f32 v51, v212, v199, v51
	v_div_scale_f32 v210, vcc, v52, v200, v52
	v_fma_f32 v212, -v204, v208, 1.0
	v_fmac_f32_e32 v208, v212, v208
	v_mul_f32_e32 v211, v210, v208
	v_fma_f32 v212, -v204, v211, v210
	v_fmac_f32_e32 v211, v212, v208
	v_fma_f32 v212, -v204, v211, v210
	v_div_fmas_f32 v212, v212, v208, v211
	v_div_fixup_f32 v52, v212, v200, v52
	v_div_scale_f32 v210, vcc, v53, v201, v53
	v_fma_f32 v212, -v205, v209, 1.0
	v_fmac_f32_e32 v209, v212, v209
	v_mul_f32_e32 v211, v210, v209
	v_fma_f32 v212, -v205, v211, v210
	v_fmac_f32_e32 v211, v212, v209
	v_fma_f32 v212, -v205, v211, v210
	v_div_fmas_f32 v212, v212, v209, v211
	v_div_fixup_f32 v53, v212, v201, v53
	v_mul_f32_e32 v198, 0xbfb8aa3b, v54
	v_mul_f32_e32 v199, 0xbfb8aa3b, v55
	v_mul_f32_e32 v200, 0xbfb8aa3b, v56
	v_mul_f32_e32 v201, 0xbfb8aa3b, v57
	v_exp_f32_e32 v198, v198
	v_exp_f32_e32 v199, v199
	v_exp_f32_e32 v200, v200
	v_exp_f32_e32 v201, v201
	s_nop 0
	v_add_f32_e32 v198, 1.0, v198
	v_add_f32_e32 v199, 1.0, v199
	v_add_f32_e32 v200, 1.0, v200
	v_add_f32_e32 v201, 1.0, v201
	v_div_scale_f32 v202, s[84:85], v198, v198, v54
	v_div_scale_f32 v203, s[84:85], v199, v199, v55
	v_div_scale_f32 v204, s[84:85], v200, v200, v56
	v_div_scale_f32 v205, s[84:85], v201, v201, v57
	v_rcp_f32_e32 v206, v202
	v_rcp_f32_e32 v207, v203
	v_rcp_f32_e32 v208, v204
	v_rcp_f32_e32 v209, v205
	s_nop 0
	v_div_scale_f32 v210, vcc, v54, v198, v54
	v_fma_f32 v212, -v202, v206, 1.0
	v_fmac_f32_e32 v206, v212, v206
	v_mul_f32_e32 v211, v210, v206
	v_fma_f32 v212, -v202, v211, v210
	v_fmac_f32_e32 v211, v212, v206
	v_fma_f32 v212, -v202, v211, v210
	v_div_fmas_f32 v212, v212, v206, v211
	v_div_fixup_f32 v54, v212, v198, v54
	v_div_scale_f32 v210, vcc, v55, v199, v55
	v_fma_f32 v212, -v203, v207, 1.0
	v_fmac_f32_e32 v207, v212, v207
	v_mul_f32_e32 v211, v210, v207
	v_fma_f32 v212, -v203, v211, v210
	v_fmac_f32_e32 v211, v212, v207
	v_fma_f32 v212, -v203, v211, v210
	v_div_fmas_f32 v212, v212, v207, v211
	v_div_fixup_f32 v55, v212, v199, v55
	v_div_scale_f32 v210, vcc, v56, v200, v56
	v_fma_f32 v212, -v204, v208, 1.0
	v_fmac_f32_e32 v208, v212, v208
	v_mul_f32_e32 v211, v210, v208
	v_fma_f32 v212, -v204, v211, v210
	v_fmac_f32_e32 v211, v212, v208
	v_fma_f32 v212, -v204, v211, v210
	v_div_fmas_f32 v212, v212, v208, v211
	v_div_fixup_f32 v56, v212, v200, v56
	v_div_scale_f32 v210, vcc, v57, v201, v57
	v_fma_f32 v212, -v205, v209, 1.0
	v_fmac_f32_e32 v209, v212, v209
	v_mul_f32_e32 v211, v210, v209
	v_fma_f32 v212, -v205, v211, v210
	v_fmac_f32_e32 v211, v212, v209
	v_fma_f32 v212, -v205, v211, v210
	v_div_fmas_f32 v212, v212, v209, v211
	v_div_fixup_f32 v57, v212, v201, v57
	v_mul_f32_e32 v198, 0xbfb8aa3b, v58
	v_mul_f32_e32 v199, 0xbfb8aa3b, v59
	v_mul_f32_e32 v200, 0xbfb8aa3b, v60
	v_mul_f32_e32 v201, 0xbfb8aa3b, v61
	v_exp_f32_e32 v198, v198
	v_exp_f32_e32 v199, v199
	v_exp_f32_e32 v200, v200
	v_exp_f32_e32 v201, v201
	s_nop 0
	v_add_f32_e32 v198, 1.0, v198
	v_add_f32_e32 v199, 1.0, v199
	v_add_f32_e32 v200, 1.0, v200
	v_add_f32_e32 v201, 1.0, v201
	v_div_scale_f32 v202, s[84:85], v198, v198, v58
	v_div_scale_f32 v203, s[84:85], v199, v199, v59
	v_div_scale_f32 v204, s[84:85], v200, v200, v60
	v_div_scale_f32 v205, s[84:85], v201, v201, v61
	v_rcp_f32_e32 v206, v202
	v_rcp_f32_e32 v207, v203
	v_rcp_f32_e32 v208, v204
	v_rcp_f32_e32 v209, v205
	s_nop 0
	v_div_scale_f32 v210, vcc, v58, v198, v58
	v_fma_f32 v212, -v202, v206, 1.0
	v_fmac_f32_e32 v206, v212, v206
	v_mul_f32_e32 v211, v210, v206
	v_fma_f32 v212, -v202, v211, v210
	v_fmac_f32_e32 v211, v212, v206
	v_fma_f32 v212, -v202, v211, v210
	v_div_fmas_f32 v212, v212, v206, v211
	v_div_fixup_f32 v58, v212, v198, v58
	v_div_scale_f32 v210, vcc, v59, v199, v59
	v_fma_f32 v212, -v203, v207, 1.0
	v_fmac_f32_e32 v207, v212, v207
	v_mul_f32_e32 v211, v210, v207
	v_fma_f32 v212, -v203, v211, v210
	v_fmac_f32_e32 v211, v212, v207
	v_fma_f32 v212, -v203, v211, v210
	v_div_fmas_f32 v212, v212, v207, v211
	v_div_fixup_f32 v59, v212, v199, v59
	v_div_scale_f32 v210, vcc, v60, v200, v60
	v_fma_f32 v212, -v204, v208, 1.0
	v_fmac_f32_e32 v208, v212, v208
	v_mul_f32_e32 v211, v210, v208
	v_fma_f32 v212, -v204, v211, v210
	v_fmac_f32_e32 v211, v212, v208
	v_fma_f32 v212, -v204, v211, v210
	v_div_fmas_f32 v212, v212, v208, v211
	v_div_fixup_f32 v60, v212, v200, v60
	v_div_scale_f32 v210, vcc, v61, v201, v61
	v_fma_f32 v212, -v205, v209, 1.0
	v_fmac_f32_e32 v209, v212, v209
	v_mul_f32_e32 v211, v210, v209
	v_fma_f32 v212, -v205, v211, v210
	v_fmac_f32_e32 v211, v212, v209
	v_fma_f32 v212, -v205, v211, v210
	v_div_fmas_f32 v212, v212, v209, v211
	v_div_fixup_f32 v61, v212, v201, v61
	v_mul_f32_e32 v198, 0xbfb8aa3b, v62
	v_mul_f32_e32 v199, 0xbfb8aa3b, v63
	v_mul_f32_e32 v200, 0xbfb8aa3b, v64
	v_mul_f32_e32 v201, 0xbfb8aa3b, v65
	v_exp_f32_e32 v198, v198
	v_exp_f32_e32 v199, v199
	v_exp_f32_e32 v200, v200
	v_exp_f32_e32 v201, v201
	s_nop 0
	v_add_f32_e32 v198, 1.0, v198
	v_add_f32_e32 v199, 1.0, v199
	v_add_f32_e32 v200, 1.0, v200
	v_add_f32_e32 v201, 1.0, v201
	v_div_scale_f32 v202, s[84:85], v198, v198, v62
	v_div_scale_f32 v203, s[84:85], v199, v199, v63
	v_div_scale_f32 v204, s[84:85], v200, v200, v64
	v_div_scale_f32 v205, s[84:85], v201, v201, v65
	v_rcp_f32_e32 v206, v202
	v_rcp_f32_e32 v207, v203
	v_rcp_f32_e32 v208, v204
	v_rcp_f32_e32 v209, v205
	s_nop 0
	v_div_scale_f32 v210, vcc, v62, v198, v62
	v_fma_f32 v212, -v202, v206, 1.0
	v_fmac_f32_e32 v206, v212, v206
	v_mul_f32_e32 v211, v210, v206
	v_fma_f32 v212, -v202, v211, v210
	v_fmac_f32_e32 v211, v212, v206
	v_fma_f32 v212, -v202, v211, v210
	v_div_fmas_f32 v212, v212, v206, v211
	v_div_fixup_f32 v62, v212, v198, v62
	v_div_scale_f32 v210, vcc, v63, v199, v63
	v_fma_f32 v212, -v203, v207, 1.0
	v_fmac_f32_e32 v207, v212, v207
	v_mul_f32_e32 v211, v210, v207
	v_fma_f32 v212, -v203, v211, v210
	v_fmac_f32_e32 v211, v212, v207
	v_fma_f32 v212, -v203, v211, v210
	v_div_fmas_f32 v212, v212, v207, v211
	v_div_fixup_f32 v63, v212, v199, v63
	v_div_scale_f32 v210, vcc, v64, v200, v64
	v_fma_f32 v212, -v204, v208, 1.0
	v_fmac_f32_e32 v208, v212, v208
	v_mul_f32_e32 v211, v210, v208
	v_fma_f32 v212, -v204, v211, v210
	v_fmac_f32_e32 v211, v212, v208
	v_fma_f32 v212, -v204, v211, v210
	v_div_fmas_f32 v212, v212, v208, v211
	v_div_fixup_f32 v64, v212, v200, v64
	v_div_scale_f32 v210, vcc, v65, v201, v65
	v_fma_f32 v212, -v205, v209, 1.0
	v_fmac_f32_e32 v209, v212, v209
	v_mul_f32_e32 v211, v210, v209
	v_fma_f32 v212, -v205, v211, v210
	v_fmac_f32_e32 v211, v212, v209
	v_fma_f32 v212, -v205, v211, v210
	v_div_fmas_f32 v212, v212, v209, v211
	v_div_fixup_f32 v65, v212, v201, v65
	v_mul_f32_e32 v198, 0xbfb8aa3b, v66
	v_mul_f32_e32 v199, 0xbfb8aa3b, v67
	v_mul_f32_e32 v200, 0xbfb8aa3b, v68
	v_mul_f32_e32 v201, 0xbfb8aa3b, v69
	v_exp_f32_e32 v198, v198
	v_exp_f32_e32 v199, v199
	v_exp_f32_e32 v200, v200
	v_exp_f32_e32 v201, v201
	s_nop 0
	v_add_f32_e32 v198, 1.0, v198
	v_add_f32_e32 v199, 1.0, v199
	v_add_f32_e32 v200, 1.0, v200
	v_add_f32_e32 v201, 1.0, v201
	v_div_scale_f32 v202, s[84:85], v198, v198, v66
	v_div_scale_f32 v203, s[84:85], v199, v199, v67
	v_div_scale_f32 v204, s[84:85], v200, v200, v68
	v_div_scale_f32 v205, s[84:85], v201, v201, v69
	v_rcp_f32_e32 v206, v202
	v_rcp_f32_e32 v207, v203
	v_rcp_f32_e32 v208, v204
	v_rcp_f32_e32 v209, v205
	s_nop 0
	v_div_scale_f32 v210, vcc, v66, v198, v66
	v_fma_f32 v212, -v202, v206, 1.0
	v_fmac_f32_e32 v206, v212, v206
	v_mul_f32_e32 v211, v210, v206
	v_fma_f32 v212, -v202, v211, v210
	v_fmac_f32_e32 v211, v212, v206
	v_fma_f32 v212, -v202, v211, v210
	v_div_fmas_f32 v212, v212, v206, v211
	v_div_fixup_f32 v66, v212, v198, v66
	v_div_scale_f32 v210, vcc, v67, v199, v67
	v_fma_f32 v212, -v203, v207, 1.0
	v_fmac_f32_e32 v207, v212, v207
	v_mul_f32_e32 v211, v210, v207
	v_fma_f32 v212, -v203, v211, v210
	v_fmac_f32_e32 v211, v212, v207
	v_fma_f32 v212, -v203, v211, v210
	v_div_fmas_f32 v212, v212, v207, v211
	v_div_fixup_f32 v67, v212, v199, v67
	v_div_scale_f32 v210, vcc, v68, v200, v68
	v_fma_f32 v212, -v204, v208, 1.0
	v_fmac_f32_e32 v208, v212, v208
	v_mul_f32_e32 v211, v210, v208
	v_fma_f32 v212, -v204, v211, v210
	v_fmac_f32_e32 v211, v212, v208
	v_fma_f32 v212, -v204, v211, v210
	v_div_fmas_f32 v212, v212, v208, v211
	v_div_fixup_f32 v68, v212, v200, v68
	v_div_scale_f32 v210, vcc, v69, v201, v69
	v_fma_f32 v212, -v205, v209, 1.0
	v_fmac_f32_e32 v209, v212, v209
	v_mul_f32_e32 v211, v210, v209
	v_fma_f32 v212, -v205, v211, v210
	v_fmac_f32_e32 v211, v212, v209
	v_fma_f32 v212, -v205, v211, v210
	v_div_fmas_f32 v212, v212, v209, v211
	v_div_fixup_f32 v69, v212, v201, v69
	v_mul_f32_e32 v198, 0xbfb8aa3b, v70
	v_mul_f32_e32 v199, 0xbfb8aa3b, v71
	v_mul_f32_e32 v200, 0xbfb8aa3b, v72
	v_mul_f32_e32 v201, 0xbfb8aa3b, v73
	v_exp_f32_e32 v198, v198
	v_exp_f32_e32 v199, v199
	v_exp_f32_e32 v200, v200
	v_exp_f32_e32 v201, v201
	s_nop 0
	v_add_f32_e32 v198, 1.0, v198
	v_add_f32_e32 v199, 1.0, v199
	v_add_f32_e32 v200, 1.0, v200
	v_add_f32_e32 v201, 1.0, v201
	v_div_scale_f32 v202, s[84:85], v198, v198, v70
	v_div_scale_f32 v203, s[84:85], v199, v199, v71
	v_div_scale_f32 v204, s[84:85], v200, v200, v72
	v_div_scale_f32 v205, s[84:85], v201, v201, v73
	v_rcp_f32_e32 v206, v202
	v_rcp_f32_e32 v207, v203
	v_rcp_f32_e32 v208, v204
	v_rcp_f32_e32 v209, v205
	s_nop 0
	v_div_scale_f32 v210, vcc, v70, v198, v70
	v_fma_f32 v212, -v202, v206, 1.0
	v_fmac_f32_e32 v206, v212, v206
	v_mul_f32_e32 v211, v210, v206
	v_fma_f32 v212, -v202, v211, v210
	v_fmac_f32_e32 v211, v212, v206
	v_fma_f32 v212, -v202, v211, v210
	v_div_fmas_f32 v212, v212, v206, v211
	v_div_fixup_f32 v70, v212, v198, v70
	v_div_scale_f32 v210, vcc, v71, v199, v71
	v_fma_f32 v212, -v203, v207, 1.0
	v_fmac_f32_e32 v207, v212, v207
	v_mul_f32_e32 v211, v210, v207
	v_fma_f32 v212, -v203, v211, v210
	v_fmac_f32_e32 v211, v212, v207
	v_fma_f32 v212, -v203, v211, v210
	v_div_fmas_f32 v212, v212, v207, v211
	v_div_fixup_f32 v71, v212, v199, v71
	v_div_scale_f32 v210, vcc, v72, v200, v72
	v_fma_f32 v212, -v204, v208, 1.0
	v_fmac_f32_e32 v208, v212, v208
	v_mul_f32_e32 v211, v210, v208
	v_fma_f32 v212, -v204, v211, v210
	v_fmac_f32_e32 v211, v212, v208
	v_fma_f32 v212, -v204, v211, v210
	v_div_fmas_f32 v212, v212, v208, v211
	v_div_fixup_f32 v72, v212, v200, v72
	v_div_scale_f32 v210, vcc, v73, v201, v73
	v_fma_f32 v212, -v205, v209, 1.0
	v_fmac_f32_e32 v209, v212, v209
	v_mul_f32_e32 v211, v210, v209
	v_fma_f32 v212, -v205, v211, v210
	v_fmac_f32_e32 v211, v212, v209
	v_fma_f32 v212, -v205, v211, v210
	v_div_fmas_f32 v212, v212, v209, v211
	v_div_fixup_f32 v73, v212, v201, v73
	v_mul_f32_e32 v198, 0xbfb8aa3b, v74
	v_mul_f32_e32 v199, 0xbfb8aa3b, v75
	v_mul_f32_e32 v200, 0xbfb8aa3b, v76
	v_mul_f32_e32 v201, 0xbfb8aa3b, v77
	v_exp_f32_e32 v198, v198
	v_exp_f32_e32 v199, v199
	v_exp_f32_e32 v200, v200
	v_exp_f32_e32 v201, v201
	s_nop 0
	v_add_f32_e32 v198, 1.0, v198
	v_add_f32_e32 v199, 1.0, v199
	v_add_f32_e32 v200, 1.0, v200
	v_add_f32_e32 v201, 1.0, v201
	v_div_scale_f32 v202, s[84:85], v198, v198, v74
	v_div_scale_f32 v203, s[84:85], v199, v199, v75
	v_div_scale_f32 v204, s[84:85], v200, v200, v76
	v_div_scale_f32 v205, s[84:85], v201, v201, v77
	v_rcp_f32_e32 v206, v202
	v_rcp_f32_e32 v207, v203
	v_rcp_f32_e32 v208, v204
	v_rcp_f32_e32 v209, v205
	s_nop 0
	v_div_scale_f32 v210, vcc, v74, v198, v74
	v_fma_f32 v212, -v202, v206, 1.0
	v_fmac_f32_e32 v206, v212, v206
	v_mul_f32_e32 v211, v210, v206
	v_fma_f32 v212, -v202, v211, v210
	v_fmac_f32_e32 v211, v212, v206
	v_fma_f32 v212, -v202, v211, v210
	v_div_fmas_f32 v212, v212, v206, v211
	v_div_fixup_f32 v74, v212, v198, v74
	v_div_scale_f32 v210, vcc, v75, v199, v75
	v_fma_f32 v212, -v203, v207, 1.0
	v_fmac_f32_e32 v207, v212, v207
	v_mul_f32_e32 v211, v210, v207
	v_fma_f32 v212, -v203, v211, v210
	v_fmac_f32_e32 v211, v212, v207
	v_fma_f32 v212, -v203, v211, v210
	v_div_fmas_f32 v212, v212, v207, v211
	v_div_fixup_f32 v75, v212, v199, v75
	v_div_scale_f32 v210, vcc, v76, v200, v76
	v_fma_f32 v212, -v204, v208, 1.0
	v_fmac_f32_e32 v208, v212, v208
	v_mul_f32_e32 v211, v210, v208
	v_fma_f32 v212, -v204, v211, v210
	v_fmac_f32_e32 v211, v212, v208
	v_fma_f32 v212, -v204, v211, v210
	v_div_fmas_f32 v212, v212, v208, v211
	v_div_fixup_f32 v76, v212, v200, v76
	v_div_scale_f32 v210, vcc, v77, v201, v77
	v_fma_f32 v212, -v205, v209, 1.0
	v_fmac_f32_e32 v209, v212, v209
	v_mul_f32_e32 v211, v210, v209
	v_fma_f32 v212, -v205, v211, v210
	v_fmac_f32_e32 v211, v212, v209
	v_fma_f32 v212, -v205, v211, v210
	v_div_fmas_f32 v212, v212, v209, v211
	v_div_fixup_f32 v77, v212, v201, v77
	v_mul_f32_e32 v198, 0xbfb8aa3b, v78
	v_mul_f32_e32 v199, 0xbfb8aa3b, v79
	v_mul_f32_e32 v200, 0xbfb8aa3b, v80
	v_mul_f32_e32 v201, 0xbfb8aa3b, v81
	v_exp_f32_e32 v198, v198
	v_exp_f32_e32 v199, v199
	v_exp_f32_e32 v200, v200
	v_exp_f32_e32 v201, v201
	s_nop 0
	v_add_f32_e32 v198, 1.0, v198
	v_add_f32_e32 v199, 1.0, v199
	v_add_f32_e32 v200, 1.0, v200
	v_add_f32_e32 v201, 1.0, v201
	v_div_scale_f32 v202, s[84:85], v198, v198, v78
	v_div_scale_f32 v203, s[84:85], v199, v199, v79
	v_div_scale_f32 v204, s[84:85], v200, v200, v80
	v_div_scale_f32 v205, s[84:85], v201, v201, v81
	v_rcp_f32_e32 v206, v202
	v_rcp_f32_e32 v207, v203
	v_rcp_f32_e32 v208, v204
	v_rcp_f32_e32 v209, v205
	s_nop 0
	v_div_scale_f32 v210, vcc, v78, v198, v78
	v_fma_f32 v212, -v202, v206, 1.0
	v_fmac_f32_e32 v206, v212, v206
	v_mul_f32_e32 v211, v210, v206
	v_fma_f32 v212, -v202, v211, v210
	v_fmac_f32_e32 v211, v212, v206
	v_fma_f32 v212, -v202, v211, v210
	v_div_fmas_f32 v212, v212, v206, v211
	v_div_fixup_f32 v78, v212, v198, v78
	v_div_scale_f32 v210, vcc, v79, v199, v79
	v_fma_f32 v212, -v203, v207, 1.0
	v_fmac_f32_e32 v207, v212, v207
	v_mul_f32_e32 v211, v210, v207
	v_fma_f32 v212, -v203, v211, v210
	v_fmac_f32_e32 v211, v212, v207
	v_fma_f32 v212, -v203, v211, v210
	v_div_fmas_f32 v212, v212, v207, v211
	v_div_fixup_f32 v79, v212, v199, v79
	v_div_scale_f32 v210, vcc, v80, v200, v80
	v_fma_f32 v212, -v204, v208, 1.0
	v_fmac_f32_e32 v208, v212, v208
	v_mul_f32_e32 v211, v210, v208
	v_fma_f32 v212, -v204, v211, v210
	v_fmac_f32_e32 v211, v212, v208
	v_fma_f32 v212, -v204, v211, v210
	v_div_fmas_f32 v212, v212, v208, v211
	v_div_fixup_f32 v80, v212, v200, v80
	v_div_scale_f32 v210, vcc, v81, v201, v81
	v_fma_f32 v212, -v205, v209, 1.0
	v_fmac_f32_e32 v209, v212, v209
	v_mul_f32_e32 v211, v210, v209
	v_fma_f32 v212, -v205, v211, v210
	v_fmac_f32_e32 v211, v212, v209
	v_fma_f32 v212, -v205, v211, v210
	v_div_fmas_f32 v212, v212, v209, v211
	v_div_fixup_f32 v81, v212, v201, v81
	v_mul_f32_e32 v198, 0xbfb8aa3b, v82
	v_mul_f32_e32 v199, 0xbfb8aa3b, v83
	v_mul_f32_e32 v200, 0xbfb8aa3b, v84
	v_mul_f32_e32 v201, 0xbfb8aa3b, v85
	v_exp_f32_e32 v198, v198
	v_exp_f32_e32 v199, v199
	v_exp_f32_e32 v200, v200
	v_exp_f32_e32 v201, v201
	s_nop 0
	v_add_f32_e32 v198, 1.0, v198
	v_add_f32_e32 v199, 1.0, v199
	v_add_f32_e32 v200, 1.0, v200
	v_add_f32_e32 v201, 1.0, v201
	v_div_scale_f32 v202, s[84:85], v198, v198, v82
	v_div_scale_f32 v203, s[84:85], v199, v199, v83
	v_div_scale_f32 v204, s[84:85], v200, v200, v84
	v_div_scale_f32 v205, s[84:85], v201, v201, v85
	v_rcp_f32_e32 v206, v202
	v_rcp_f32_e32 v207, v203
	v_rcp_f32_e32 v208, v204
	v_rcp_f32_e32 v209, v205
	s_nop 0
	v_div_scale_f32 v210, vcc, v82, v198, v82
	v_fma_f32 v212, -v202, v206, 1.0
	v_fmac_f32_e32 v206, v212, v206
	v_mul_f32_e32 v211, v210, v206
	v_fma_f32 v212, -v202, v211, v210
	v_fmac_f32_e32 v211, v212, v206
	v_fma_f32 v212, -v202, v211, v210
	v_div_fmas_f32 v212, v212, v206, v211
	v_div_fixup_f32 v82, v212, v198, v82
	v_div_scale_f32 v210, vcc, v83, v199, v83
	v_fma_f32 v212, -v203, v207, 1.0
	v_fmac_f32_e32 v207, v212, v207
	v_mul_f32_e32 v211, v210, v207
	v_fma_f32 v212, -v203, v211, v210
	v_fmac_f32_e32 v211, v212, v207
	v_fma_f32 v212, -v203, v211, v210
	v_div_fmas_f32 v212, v212, v207, v211
	v_div_fixup_f32 v83, v212, v199, v83
	v_div_scale_f32 v210, vcc, v84, v200, v84
	v_fma_f32 v212, -v204, v208, 1.0
	v_fmac_f32_e32 v208, v212, v208
	v_mul_f32_e32 v211, v210, v208
	v_fma_f32 v212, -v204, v211, v210
	v_fmac_f32_e32 v211, v212, v208
	v_fma_f32 v212, -v204, v211, v210
	v_div_fmas_f32 v212, v212, v208, v211
	v_div_fixup_f32 v84, v212, v200, v84
	v_div_scale_f32 v210, vcc, v85, v201, v85
	v_fma_f32 v212, -v205, v209, 1.0
	v_fmac_f32_e32 v209, v212, v209
	v_mul_f32_e32 v211, v210, v209
	v_fma_f32 v212, -v205, v211, v210
	v_fmac_f32_e32 v211, v212, v209
	v_fma_f32 v212, -v205, v211, v210
	v_div_fmas_f32 v212, v212, v209, v211
	v_div_fixup_f32 v85, v212, v201, v85
	v_mul_f32_e32 v198, 0xbfb8aa3b, v86
	v_mul_f32_e32 v199, 0xbfb8aa3b, v87
	v_mul_f32_e32 v200, 0xbfb8aa3b, v88
	v_mul_f32_e32 v201, 0xbfb8aa3b, v89
	v_exp_f32_e32 v198, v198
	v_exp_f32_e32 v199, v199
	v_exp_f32_e32 v200, v200
	v_exp_f32_e32 v201, v201
	s_nop 0
	v_add_f32_e32 v198, 1.0, v198
	v_add_f32_e32 v199, 1.0, v199
	v_add_f32_e32 v200, 1.0, v200
	v_add_f32_e32 v201, 1.0, v201
	v_div_scale_f32 v202, s[84:85], v198, v198, v86
	v_div_scale_f32 v203, s[84:85], v199, v199, v87
	v_div_scale_f32 v204, s[84:85], v200, v200, v88
	v_div_scale_f32 v205, s[84:85], v201, v201, v89
	v_rcp_f32_e32 v206, v202
	v_rcp_f32_e32 v207, v203
	v_rcp_f32_e32 v208, v204
	v_rcp_f32_e32 v209, v205
	s_nop 0
	v_div_scale_f32 v210, vcc, v86, v198, v86
	v_fma_f32 v212, -v202, v206, 1.0
	v_fmac_f32_e32 v206, v212, v206
	v_mul_f32_e32 v211, v210, v206
	v_fma_f32 v212, -v202, v211, v210
	v_fmac_f32_e32 v211, v212, v206
	v_fma_f32 v212, -v202, v211, v210
	v_div_fmas_f32 v212, v212, v206, v211
	v_div_fixup_f32 v86, v212, v198, v86
	v_div_scale_f32 v210, vcc, v87, v199, v87
	v_fma_f32 v212, -v203, v207, 1.0
	v_fmac_f32_e32 v207, v212, v207
	v_mul_f32_e32 v211, v210, v207
	v_fma_f32 v212, -v203, v211, v210
	v_fmac_f32_e32 v211, v212, v207
	v_fma_f32 v212, -v203, v211, v210
	v_div_fmas_f32 v212, v212, v207, v211
	v_div_fixup_f32 v87, v212, v199, v87
	v_div_scale_f32 v210, vcc, v88, v200, v88
	v_fma_f32 v212, -v204, v208, 1.0
	v_fmac_f32_e32 v208, v212, v208
	v_mul_f32_e32 v211, v210, v208
	v_fma_f32 v212, -v204, v211, v210
	v_fmac_f32_e32 v211, v212, v208
	v_fma_f32 v212, -v204, v211, v210
	v_div_fmas_f32 v212, v212, v208, v211
	v_div_fixup_f32 v88, v212, v200, v88
	v_div_scale_f32 v210, vcc, v89, v201, v89
	v_fma_f32 v212, -v205, v209, 1.0
	v_fmac_f32_e32 v209, v212, v209
	v_mul_f32_e32 v211, v210, v209
	v_fma_f32 v212, -v205, v211, v210
	v_fmac_f32_e32 v211, v212, v209
	v_fma_f32 v212, -v205, v211, v210
	v_div_fmas_f32 v212, v212, v209, v211
	v_div_fixup_f32 v89, v212, v201, v89
	v_mul_f32_e32 v198, 0xbfb8aa3b, v90
	v_mul_f32_e32 v199, 0xbfb8aa3b, v91
	v_mul_f32_e32 v200, 0xbfb8aa3b, v92
	v_mul_f32_e32 v201, 0xbfb8aa3b, v93
	v_exp_f32_e32 v198, v198
	v_exp_f32_e32 v199, v199
	v_exp_f32_e32 v200, v200
	v_exp_f32_e32 v201, v201
	s_nop 0
	v_add_f32_e32 v198, 1.0, v198
	v_add_f32_e32 v199, 1.0, v199
	v_add_f32_e32 v200, 1.0, v200
	v_add_f32_e32 v201, 1.0, v201
	v_div_scale_f32 v202, s[84:85], v198, v198, v90
	v_div_scale_f32 v203, s[84:85], v199, v199, v91
	v_div_scale_f32 v204, s[84:85], v200, v200, v92
	v_div_scale_f32 v205, s[84:85], v201, v201, v93
	v_rcp_f32_e32 v206, v202
	v_rcp_f32_e32 v207, v203
	v_rcp_f32_e32 v208, v204
	v_rcp_f32_e32 v209, v205
	s_nop 0
	v_div_scale_f32 v210, vcc, v90, v198, v90
	v_fma_f32 v212, -v202, v206, 1.0
	v_fmac_f32_e32 v206, v212, v206
	v_mul_f32_e32 v211, v210, v206
	v_fma_f32 v212, -v202, v211, v210
	v_fmac_f32_e32 v211, v212, v206
	v_fma_f32 v212, -v202, v211, v210
	v_div_fmas_f32 v212, v212, v206, v211
	v_div_fixup_f32 v90, v212, v198, v90
	v_div_scale_f32 v210, vcc, v91, v199, v91
	v_fma_f32 v212, -v203, v207, 1.0
	v_fmac_f32_e32 v207, v212, v207
	v_mul_f32_e32 v211, v210, v207
	v_fma_f32 v212, -v203, v211, v210
	v_fmac_f32_e32 v211, v212, v207
	v_fma_f32 v212, -v203, v211, v210
	v_div_fmas_f32 v212, v212, v207, v211
	v_div_fixup_f32 v91, v212, v199, v91
	v_div_scale_f32 v210, vcc, v92, v200, v92
	v_fma_f32 v212, -v204, v208, 1.0
	v_fmac_f32_e32 v208, v212, v208
	v_mul_f32_e32 v211, v210, v208
	v_fma_f32 v212, -v204, v211, v210
	v_fmac_f32_e32 v211, v212, v208
	v_fma_f32 v212, -v204, v211, v210
	v_div_fmas_f32 v212, v212, v208, v211
	v_div_fixup_f32 v92, v212, v200, v92
	v_div_scale_f32 v210, vcc, v93, v201, v93
	v_fma_f32 v212, -v205, v209, 1.0
	v_fmac_f32_e32 v209, v212, v209
	v_mul_f32_e32 v211, v210, v209
	v_fma_f32 v212, -v205, v211, v210
	v_fmac_f32_e32 v211, v212, v209
	v_fma_f32 v212, -v205, v211, v210
	v_div_fmas_f32 v212, v212, v209, v211
	v_div_fixup_f32 v93, v212, v201, v93
	v_mul_f32_e32 v198, 0xbfb8aa3b, v94
	v_mul_f32_e32 v199, 0xbfb8aa3b, v95
	v_mul_f32_e32 v200, 0xbfb8aa3b, v96
	v_mul_f32_e32 v201, 0xbfb8aa3b, v97
	v_exp_f32_e32 v198, v198
	v_exp_f32_e32 v199, v199
	v_exp_f32_e32 v200, v200
	v_exp_f32_e32 v201, v201
	s_nop 0
	v_add_f32_e32 v198, 1.0, v198
	v_add_f32_e32 v199, 1.0, v199
	v_add_f32_e32 v200, 1.0, v200
	v_add_f32_e32 v201, 1.0, v201
	v_div_scale_f32 v202, s[84:85], v198, v198, v94
	v_div_scale_f32 v203, s[84:85], v199, v199, v95
	v_div_scale_f32 v204, s[84:85], v200, v200, v96
	v_div_scale_f32 v205, s[84:85], v201, v201, v97
	v_rcp_f32_e32 v206, v202
	v_rcp_f32_e32 v207, v203
	v_rcp_f32_e32 v208, v204
	v_rcp_f32_e32 v209, v205
	s_nop 0
	v_div_scale_f32 v210, vcc, v94, v198, v94
	v_fma_f32 v212, -v202, v206, 1.0
	v_fmac_f32_e32 v206, v212, v206
	v_mul_f32_e32 v211, v210, v206
	v_fma_f32 v212, -v202, v211, v210
	v_fmac_f32_e32 v211, v212, v206
	v_fma_f32 v212, -v202, v211, v210
	v_div_fmas_f32 v212, v212, v206, v211
	v_div_fixup_f32 v94, v212, v198, v94
	v_div_scale_f32 v210, vcc, v95, v199, v95
	v_fma_f32 v212, -v203, v207, 1.0
	v_fmac_f32_e32 v207, v212, v207
	v_mul_f32_e32 v211, v210, v207
	v_fma_f32 v212, -v203, v211, v210
	v_fmac_f32_e32 v211, v212, v207
	v_fma_f32 v212, -v203, v211, v210
	v_div_fmas_f32 v212, v212, v207, v211
	v_div_fixup_f32 v95, v212, v199, v95
	v_div_scale_f32 v210, vcc, v96, v200, v96
	v_fma_f32 v212, -v204, v208, 1.0
	v_fmac_f32_e32 v208, v212, v208
	v_mul_f32_e32 v211, v210, v208
	v_fma_f32 v212, -v204, v211, v210
	v_fmac_f32_e32 v211, v212, v208
	v_fma_f32 v212, -v204, v211, v210
	v_div_fmas_f32 v212, v212, v208, v211
	v_div_fixup_f32 v96, v212, v200, v96
	v_div_scale_f32 v210, vcc, v97, v201, v97
	v_fma_f32 v212, -v205, v209, 1.0
	v_fmac_f32_e32 v209, v212, v209
	v_mul_f32_e32 v211, v210, v209
	v_fma_f32 v212, -v205, v211, v210
	v_fmac_f32_e32 v211, v212, v209
	v_fma_f32 v212, -v205, v211, v210
	v_div_fmas_f32 v212, v212, v209, v211
	v_div_fixup_f32 v97, v212, v201, v97
	v_and_b32_e32 v223, 31, v0
	v_mul_u32_u24_e32 v220, 0x110, v223
	v_bfe_u32 v223, v0, 5, 1
	v_lshl_add_u32 v220, v223, 4, v220
	v_bfe_u32 v224, v0, 6, 2
	v_mul_u32_u24_e32 v223, 0x2200, v224
	v_add_u32_e32 v220, v220, v223
	v_bfe_u32 v222, v0, 4, 2
	v_mul_u32_u24_e32 v221, 0x110, v222
	v_add_u32_e32 v221, v221, v223
	v_and_b32_e32 v223, 15, v0
	v_lshl_add_u32 v221, v223, 4, v221
	s_lshr_b32 s85, s56, 6
	s_lshl_b32 s85, s85, 8
	s_sub_u32 s85, s85, 0x680
	s_and_b32 s84, s56, 63
	s_mulk_i32 s84, 0xc0
	v_lshrrev_b32_e32 v224, 1, v224
	v_mul_u32_u24_e32 v224, 0x60, v224
	v_add3_u32 v222, v222, v224, s84
	v_lshlrev_b32_e32 v222, 11, v222
	v_lshl_add_u32 v222, v223, 3, v222
	v_bfe_u32 v223, v0, 6, 1
	v_lshl_add_u32 v222, v223, 7, v222
	v_add_u32_e32 v222, s85, v222
	ds_write_b128 v220, v[82:85]
	ds_write_b128 v220, v[86:89] offset:32
	ds_write_b128 v220, v[90:93] offset:64
	ds_write_b128 v220, v[94:97] offset:96
	ds_write_b128 v220, v[66:69] offset:128
	ds_write_b128 v220, v[70:73] offset:160
	ds_write_b128 v220, v[74:77] offset:192
	ds_write_b128 v220, v[78:81] offset:224
	v_mov_b32_e32 v230, v222
	v_add_u32_e32 v231, 0x2000, v222
	v_add_u32_e32 v232, 0x4000, v222
	v_add_u32_e32 v233, 0x6000, v222
	v_add_u32_e32 v234, 0x8000, v222
	v_add_u32_e32 v235, 0xa000, v222
	v_add_u32_e32 v236, 0xc000, v222
	v_add_u32_e32 v237, 0xe000, v222
	s_waitcnt lgkmcnt(0)
	ds_read_b128 v[82:85], v221
	ds_read_b128 v[86:89], v221 offset:1088
	ds_read_b128 v[90:93], v221 offset:2176
	ds_read_b128 v[94:97], v221 offset:3264
	ds_read_b128 v[66:69], v221 offset:4352
	ds_read_b128 v[70:73], v221 offset:5440
	ds_read_b128 v[74:77], v221 offset:6528
	ds_read_b128 v[78:81], v221 offset:7616
	s_waitcnt lgkmcnt(7)
	v_cvt_pk_bf16_f32 v82, v82, v83
	v_cvt_pk_bf16_f32 v83, v84, v85
	global_store_dwordx2 v230, v[82:83], s[82:83]
	s_waitcnt lgkmcnt(6)
	v_cvt_pk_bf16_f32 v86, v86, v87
	v_cvt_pk_bf16_f32 v87, v88, v89
	global_store_dwordx2 v231, v[86:87], s[82:83]
	s_waitcnt lgkmcnt(5)
	v_cvt_pk_bf16_f32 v90, v90, v91
	v_cvt_pk_bf16_f32 v91, v92, v93
	global_store_dwordx2 v232, v[90:91], s[82:83]
	s_waitcnt lgkmcnt(4)
	v_cvt_pk_bf16_f32 v94, v94, v95
	v_cvt_pk_bf16_f32 v95, v96, v97
	global_store_dwordx2 v233, v[94:95], s[82:83]
	s_waitcnt lgkmcnt(3)
	v_cvt_pk_bf16_f32 v66, v66, v67
	v_cvt_pk_bf16_f32 v67, v68, v69
	global_store_dwordx2 v234, v[66:67], s[82:83]
	s_waitcnt lgkmcnt(2)
	v_cvt_pk_bf16_f32 v70, v70, v71
	v_cvt_pk_bf16_f32 v71, v72, v73
	global_store_dwordx2 v235, v[70:71], s[82:83]
	s_waitcnt lgkmcnt(1)
	v_cvt_pk_bf16_f32 v74, v74, v75
	v_cvt_pk_bf16_f32 v75, v76, v77
	global_store_dwordx2 v236, v[74:75], s[82:83]
	s_waitcnt lgkmcnt(0)
	v_cvt_pk_bf16_f32 v78, v78, v79
	v_cvt_pk_bf16_f32 v79, v80, v81
	global_store_dwordx2 v237, v[78:79], s[82:83]
	ds_write_b128 v220, v[50:53]
	ds_write_b128 v220, v[54:57] offset:32
	ds_write_b128 v220, v[58:61] offset:64
	ds_write_b128 v220, v[62:65] offset:96
	ds_write_b128 v220, v[34:37] offset:128
	ds_write_b128 v220, v[38:41] offset:160
	ds_write_b128 v220, v[42:45] offset:192
	ds_write_b128 v220, v[46:49] offset:224
	v_add_u32_e32 v230, 0x10000, v222
	v_add_u32_e32 v231, 0x12000, v222
	v_add_u32_e32 v232, 0x14000, v222
	v_add_u32_e32 v233, 0x16000, v222
	v_add_u32_e32 v234, 0x18000, v222
	v_add_u32_e32 v235, 0x1a000, v222
	v_add_u32_e32 v236, 0x1c000, v222
	v_add_u32_e32 v237, 0x1e000, v222
	s_waitcnt lgkmcnt(0)
	ds_read_b128 v[50:53], v221
	ds_read_b128 v[54:57], v221 offset:1088
	ds_read_b128 v[58:61], v221 offset:2176
	ds_read_b128 v[62:65], v221 offset:3264
	ds_read_b128 v[34:37], v221 offset:4352
	ds_read_b128 v[38:41], v221 offset:5440
	ds_read_b128 v[42:45], v221 offset:6528
	ds_read_b128 v[46:49], v221 offset:7616
	s_waitcnt lgkmcnt(7)
	v_cvt_pk_bf16_f32 v50, v50, v51
	v_cvt_pk_bf16_f32 v51, v52, v53
	global_store_dwordx2 v230, v[50:51], s[82:83]
	s_waitcnt lgkmcnt(6)
	v_cvt_pk_bf16_f32 v54, v54, v55
	v_cvt_pk_bf16_f32 v55, v56, v57
	global_store_dwordx2 v231, v[54:55], s[82:83]
	s_waitcnt lgkmcnt(5)
	v_cvt_pk_bf16_f32 v58, v58, v59
	v_cvt_pk_bf16_f32 v59, v60, v61
	global_store_dwordx2 v232, v[58:59], s[82:83]
	s_waitcnt lgkmcnt(4)
	v_cvt_pk_bf16_f32 v62, v62, v63
	v_cvt_pk_bf16_f32 v63, v64, v65
	global_store_dwordx2 v233, v[62:63], s[82:83]
	s_waitcnt lgkmcnt(3)
	v_cvt_pk_bf16_f32 v34, v34, v35
	v_cvt_pk_bf16_f32 v35, v36, v37
	global_store_dwordx2 v234, v[34:35], s[82:83]
	s_waitcnt lgkmcnt(2)
	v_cvt_pk_bf16_f32 v38, v38, v39
	v_cvt_pk_bf16_f32 v39, v40, v41
	global_store_dwordx2 v235, v[38:39], s[82:83]
	s_waitcnt lgkmcnt(1)
	v_cvt_pk_bf16_f32 v42, v42, v43
	v_cvt_pk_bf16_f32 v43, v44, v45
	global_store_dwordx2 v236, v[42:43], s[82:83]
	s_waitcnt lgkmcnt(0)
	v_cvt_pk_bf16_f32 v46, v46, v47
	v_cvt_pk_bf16_f32 v47, v48, v49
	global_store_dwordx2 v237, v[46:47], s[82:83]
	ds_write_b128 v220, v[18:21]
	ds_write_b128 v220, v[22:25] offset:32
	ds_write_b128 v220, v[26:29] offset:64
	ds_write_b128 v220, v[30:33] offset:96
	ds_write_b128 v220, v[2:5] offset:128
	ds_write_b128 v220, v[6:9] offset:160
	ds_write_b128 v220, v[10:13] offset:192
	ds_write_b128 v220, v[14:17] offset:224
	v_add_u32_e32 v230, 0x20000, v222
	v_add_u32_e32 v231, 0x22000, v222
	v_add_u32_e32 v232, 0x24000, v222
	v_add_u32_e32 v233, 0x26000, v222
	v_add_u32_e32 v234, 0x28000, v222
	v_add_u32_e32 v235, 0x2a000, v222
	v_add_u32_e32 v236, 0x2c000, v222
	v_add_u32_e32 v237, 0x2e000, v222
	s_waitcnt lgkmcnt(0)
	ds_read_b128 v[18:21], v221
	ds_read_b128 v[22:25], v221 offset:1088
	ds_read_b128 v[26:29], v221 offset:2176
	ds_read_b128 v[30:33], v221 offset:3264
	ds_read_b128 v[2:5], v221 offset:4352
	ds_read_b128 v[6:9], v221 offset:5440
	ds_read_b128 v[10:13], v221 offset:6528
	ds_read_b128 v[14:17], v221 offset:7616
	s_waitcnt lgkmcnt(7)
	v_cvt_pk_bf16_f32 v18, v18, v19
	v_cvt_pk_bf16_f32 v19, v20, v21
	global_store_dwordx2 v230, v[18:19], s[82:83]
	s_waitcnt lgkmcnt(6)
	v_cvt_pk_bf16_f32 v22, v22, v23
	v_cvt_pk_bf16_f32 v23, v24, v25
	global_store_dwordx2 v231, v[22:23], s[82:83]
	s_waitcnt lgkmcnt(5)
	v_cvt_pk_bf16_f32 v26, v26, v27
	v_cvt_pk_bf16_f32 v27, v28, v29
	global_store_dwordx2 v232, v[26:27], s[82:83]
	s_waitcnt lgkmcnt(4)
	v_cvt_pk_bf16_f32 v30, v30, v31
	v_cvt_pk_bf16_f32 v31, v32, v33
	global_store_dwordx2 v233, v[30:31], s[82:83]
	s_waitcnt lgkmcnt(3)
	v_cvt_pk_bf16_f32 v2, v2, v3
	v_cvt_pk_bf16_f32 v3, v4, v5
	global_store_dwordx2 v234, v[2:3], s[82:83]
	s_waitcnt lgkmcnt(2)
	v_cvt_pk_bf16_f32 v6, v6, v7
	v_cvt_pk_bf16_f32 v7, v8, v9
	global_store_dwordx2 v235, v[6:7], s[82:83]
	s_waitcnt lgkmcnt(1)
	v_cvt_pk_bf16_f32 v10, v10, v11
	v_cvt_pk_bf16_f32 v11, v12, v13
	global_store_dwordx2 v236, v[10:11], s[82:83]
	s_waitcnt lgkmcnt(0)
	v_cvt_pk_bf16_f32 v14, v14, v15
	v_cvt_pk_bf16_f32 v15, v16, v17
	global_store_dwordx2 v237, v[14:15], s[82:83]
	s_barrier
	s_mov_b64 s[10:11], exec
	s_branch .LBB0_625
G1E_ph7_U:
	s_load_dwordx2 s[82:83], s[0:1], 0x120
	v_and_b32_e32 v223, 31, v0
	v_mul_u32_u24_e32 v220, 0x110, v223
	v_bfe_u32 v223, v0, 5, 1
	v_lshl_add_u32 v220, v223, 4, v220
	v_bfe_u32 v224, v0, 6, 2
	v_mul_u32_u24_e32 v223, 0x2200, v224
	v_add_u32_e32 v220, v220, v223
	v_bfe_u32 v222, v0, 4, 2
	v_mul_u32_u24_e32 v221, 0x110, v222
	v_add_u32_e32 v221, v221, v223
	v_and_b32_e32 v223, 15, v0
	v_lshl_add_u32 v221, v223, 4, v221
	s_lshr_b32 s85, s56, 6
	s_lshl_b32 s85, s85, 9
	s_and_b32 s84, s56, 63
	s_mulk_i32 s84, 0xc0
	v_lshrrev_b32_e32 v224, 1, v224
	v_mul_u32_u24_e32 v224, 0x60, v224
	v_add3_u32 v222, v222, v224, s84
	v_mul_u32_u24_e32 v222, 0xc00, v222
	v_lshl_add_u32 v222, v223, 4, v222
	v_bfe_u32 v223, v0, 6, 1
	v_lshl_add_u32 v222, v223, 8, v222
	v_add_u32_e32 v222, s85, v222
	ds_write_b128 v220, v[82:85]
	ds_write_b128 v220, v[86:89] offset:32
	ds_write_b128 v220, v[90:93] offset:64
	ds_write_b128 v220, v[94:97] offset:96
	ds_write_b128 v220, v[66:69] offset:128
	ds_write_b128 v220, v[70:73] offset:160
	ds_write_b128 v220, v[74:77] offset:192
	ds_write_b128 v220, v[78:81] offset:224
	v_mov_b32_e32 v230, v222
	v_add_u32_e32 v231, 0x3000, v222
	v_add_u32_e32 v232, 0x6000, v222
	v_add_u32_e32 v233, 0x9000, v222
	v_add_u32_e32 v234, 0xc000, v222
	v_add_u32_e32 v235, 0xf000, v222
	v_add_u32_e32 v236, 0x12000, v222
	v_add_u32_e32 v237, 0x15000, v222
	s_waitcnt lgkmcnt(0)
	ds_read_b128 v[82:85], v221
	ds_read_b128 v[86:89], v221 offset:1088
	ds_read_b128 v[90:93], v221 offset:2176
	ds_read_b128 v[94:97], v221 offset:3264
	ds_read_b128 v[66:69], v221 offset:4352
	ds_read_b128 v[70:73], v221 offset:5440
	ds_read_b128 v[74:77], v221 offset:6528
	ds_read_b128 v[78:81], v221 offset:7616
	s_waitcnt lgkmcnt(7)
	global_store_dwordx4 v230, v[82:85], s[82:83] sc1
	s_waitcnt lgkmcnt(6)
	global_store_dwordx4 v231, v[86:89], s[82:83] sc1
	s_waitcnt lgkmcnt(5)
	global_store_dwordx4 v232, v[90:93], s[82:83] sc1
	s_waitcnt lgkmcnt(4)
	global_store_dwordx4 v233, v[94:97], s[82:83] sc1
	s_waitcnt lgkmcnt(3)
	global_store_dwordx4 v234, v[66:69], s[82:83] sc1
	s_waitcnt lgkmcnt(2)
	global_store_dwordx4 v235, v[70:73], s[82:83] sc1
	s_waitcnt lgkmcnt(1)
	global_store_dwordx4 v236, v[74:77], s[82:83] sc1
	s_waitcnt lgkmcnt(0)
	global_store_dwordx4 v237, v[78:81], s[82:83] sc1
	ds_write_b128 v220, v[50:53]
	ds_write_b128 v220, v[54:57] offset:32
	ds_write_b128 v220, v[58:61] offset:64
	ds_write_b128 v220, v[62:65] offset:96
	ds_write_b128 v220, v[34:37] offset:128
	ds_write_b128 v220, v[38:41] offset:160
	ds_write_b128 v220, v[42:45] offset:192
	ds_write_b128 v220, v[46:49] offset:224
	v_add_u32_e32 v230, 0x18000, v222
	v_add_u32_e32 v231, 0x1b000, v222
	v_add_u32_e32 v232, 0x1e000, v222
	v_add_u32_e32 v233, 0x21000, v222
	v_add_u32_e32 v234, 0x24000, v222
	v_add_u32_e32 v235, 0x27000, v222
	v_add_u32_e32 v236, 0x2a000, v222
	v_add_u32_e32 v237, 0x2d000, v222
	s_waitcnt lgkmcnt(0)
	ds_read_b128 v[50:53], v221
	ds_read_b128 v[54:57], v221 offset:1088
	ds_read_b128 v[58:61], v221 offset:2176
	ds_read_b128 v[62:65], v221 offset:3264
	ds_read_b128 v[34:37], v221 offset:4352
	ds_read_b128 v[38:41], v221 offset:5440
	ds_read_b128 v[42:45], v221 offset:6528
	ds_read_b128 v[46:49], v221 offset:7616
	s_waitcnt lgkmcnt(7)
	global_store_dwordx4 v230, v[50:53], s[82:83] sc1
	s_waitcnt lgkmcnt(6)
	global_store_dwordx4 v231, v[54:57], s[82:83] sc1
	s_waitcnt lgkmcnt(5)
	global_store_dwordx4 v232, v[58:61], s[82:83] sc1
	s_waitcnt lgkmcnt(4)
	global_store_dwordx4 v233, v[62:65], s[82:83] sc1
	s_waitcnt lgkmcnt(3)
	global_store_dwordx4 v234, v[34:37], s[82:83] sc1
	s_waitcnt lgkmcnt(2)
	global_store_dwordx4 v235, v[38:41], s[82:83] sc1
	s_waitcnt lgkmcnt(1)
	global_store_dwordx4 v236, v[42:45], s[82:83] sc1
	s_waitcnt lgkmcnt(0)
	global_store_dwordx4 v237, v[46:49], s[82:83] sc1
	ds_write_b128 v220, v[18:21]
	ds_write_b128 v220, v[22:25] offset:32
	ds_write_b128 v220, v[26:29] offset:64
	ds_write_b128 v220, v[30:33] offset:96
	ds_write_b128 v220, v[2:5] offset:128
	ds_write_b128 v220, v[6:9] offset:160
	ds_write_b128 v220, v[10:13] offset:192
	ds_write_b128 v220, v[14:17] offset:224
	v_add_u32_e32 v230, 0x30000, v222
	v_add_u32_e32 v231, 0x33000, v222
	v_add_u32_e32 v232, 0x36000, v222
	v_add_u32_e32 v233, 0x39000, v222
	v_add_u32_e32 v234, 0x3c000, v222
	v_add_u32_e32 v235, 0x3f000, v222
	v_add_u32_e32 v236, 0x42000, v222
	v_add_u32_e32 v237, 0x45000, v222
	s_waitcnt lgkmcnt(0)
	ds_read_b128 v[18:21], v221
	ds_read_b128 v[22:25], v221 offset:1088
	ds_read_b128 v[26:29], v221 offset:2176
	ds_read_b128 v[30:33], v221 offset:3264
	ds_read_b128 v[2:5], v221 offset:4352
	ds_read_b128 v[6:9], v221 offset:5440
	ds_read_b128 v[10:13], v221 offset:6528
	ds_read_b128 v[14:17], v221 offset:7616
	s_waitcnt lgkmcnt(7)
	global_store_dwordx4 v230, v[18:21], s[82:83] sc1
	s_waitcnt lgkmcnt(6)
	global_store_dwordx4 v231, v[22:25], s[82:83] sc1
	s_waitcnt lgkmcnt(5)
	global_store_dwordx4 v232, v[26:29], s[82:83] sc1
	s_waitcnt lgkmcnt(4)
	global_store_dwordx4 v233, v[30:33], s[82:83] sc1
	s_waitcnt lgkmcnt(3)
	global_store_dwordx4 v234, v[2:5], s[82:83] sc1
	s_waitcnt lgkmcnt(2)
	global_store_dwordx4 v235, v[6:9], s[82:83] sc1
	s_waitcnt lgkmcnt(1)
	global_store_dwordx4 v236, v[10:13], s[82:83] sc1
	s_waitcnt lgkmcnt(0)
	global_store_dwordx4 v237, v[14:17], s[82:83] sc1
	s_barrier
	s_mov_b64 s[10:11], exec
	s_branch .LBB0_625
G1E_ph7_ORIG:
	s_waitcnt lgkmcnt(0)
	v_add_u32_e32 v140, s4, v154
	v_add_u32_e32 v98, 0xfffff000, v140
	v_lshrrev_b32_e32 v98, 11, v98
	v_or_b32_e32 v138, s5, v162
	v_ashrrev_i32_e32 v141, 31, v140
	v_mul_u32_u24_e32 v98, 0x900, v98
	v_and_b32_e32 v139, 0x7ff, v140
	v_cmp_lt_i32_e64 s[6:7], s48, v140
	v_cmp_gt_i32_e64 s[8:9], s3, v140
	v_add3_u32 v139, v139, v98, s49
	v_mad_i64_i32 v[152:153], s[4:5], v140, s50, 0
	v_cmp_gt_i32_e64 s[10:11], s51, v138
	v_lshlrev_b64 v[142:143], 11, v[140:141]
	v_lshlrev_b64 v[144:145], 6, v[140:141]
	s_and_saveexec_b64 s[4:5], s[10:11]
	s_cbranch_execz .LBB0_656
	v_cmp_lt_i32_e32 vcc, s52, v138
	s_and_saveexec_b64 s[40:41], vcc
	s_xor_b64 s[40:41], exec, s[40:41]
	s_cbranch_execz .LBB0_654
	v_cmp_lt_u32_e32 vcc, s53, v138
	s_and_saveexec_b64 s[42:43], vcc
	s_xor_b64 s[42:43], exec, s[42:43]
	s_cbranch_execz .LBB0_632
	v_mul_f32_e32 v98, 0xbfb8aa3b, v82
	v_exp_f32_e32 v190, v98
	v_mul_f32_e32 v98, 0xbfb8aa3b, v83
	v_exp_f32_e32 v191, v98
	v_or_b32_e32 v98, v138, v104
	v_pk_add_f32 v[190:191], v[190:191], 1.0 op_sel_hi:[1,0]
	s_nop 0
	v_div_scale_f32 v141, s[44:45], v191, v191, v83
	v_rcp_f32_e32 v192, v141
	v_div_scale_f32 v193, vcc, v83, v191, v83
	v_fma_f32 v194, -v141, v192, 1.0
	v_fmac_f32_e32 v192, v194, v192
	v_mul_f32_e32 v194, v193, v192
	v_fma_f32 v195, -v141, v194, v193
	v_fmac_f32_e32 v194, v195, v192
	v_div_scale_f32 v195, s[44:45], v190, v190, v82
	v_rcp_f32_e32 v196, v195
	v_fma_f32 v141, -v141, v194, v193
	v_div_fmas_f32 v141, v141, v192, v194
	v_mul_f32_e32 v192, 0xbfb8aa3b, v84
	v_mul_f32_e32 v193, 0xbfb8aa3b, v85
	v_exp_f32_e32 v192, v192
	v_exp_f32_e32 v193, v193
	v_div_fixup_f32 v83, v141, v191, v83
	v_fma_f32 v141, -v195, v196, 1.0
	v_fmac_f32_e32 v196, v141, v196
	v_div_scale_f32 v141, vcc, v82, v190, v82
	v_mul_f32_e32 v191, v141, v196
	v_fma_f32 v194, -v195, v191, v141
	v_pk_add_f32 v[192:193], v[192:193], 1.0 op_sel_hi:[1,0]
	v_fmac_f32_e32 v191, v194, v196
	v_div_scale_f32 v194, s[44:45], v193, v193, v85
	v_fma_f32 v141, -v195, v191, v141
	v_rcp_f32_e32 v195, v194
	v_div_fmas_f32 v141, v141, v196, v191
	v_div_fixup_f32 v82, v141, v190, v82
	v_cvt_pk_bf16_f32 v190, v82, v83
	v_fma_f32 v82, -v194, v195, 1.0
	v_fmac_f32_e32 v195, v82, v195
	v_div_scale_f32 v82, vcc, v85, v193, v85
	v_mul_f32_e32 v83, v82, v195
	v_fma_f32 v141, -v194, v83, v82
	v_fmac_f32_e32 v83, v141, v195
	v_div_scale_f32 v141, s[44:45], v192, v192, v84
	v_rcp_f32_e32 v191, v141
	v_fma_f32 v82, -v194, v83, v82
	v_div_fmas_f32 v82, v82, v195, v83
	v_div_fixup_f32 v85, v82, v193, v85
	v_fma_f32 v82, -v141, v191, 1.0
	v_fmac_f32_e32 v191, v82, v191
	v_div_scale_f32 v82, vcc, v84, v192, v84
	v_mul_f32_e32 v193, v82, v191
	v_fma_f32 v83, -v141, v193, v82
	v_fmac_f32_e32 v193, v83, v191
	v_fma_f32 v141, -v141, v193, v82
	v_mul_f32_e32 v82, 0xbfb8aa3b, v86
	v_mul_f32_e32 v83, 0xbfb8aa3b, v87
	v_exp_f32_e32 v82, v82
	v_exp_f32_e32 v83, v83
	v_div_fmas_f32 v141, v141, v191, v193
	v_div_fixup_f32 v84, v141, v192, v84
	v_cvt_pk_bf16_f32 v191, v84, v85
	v_pk_add_f32 v[84:85], v[82:83], 1.0 op_sel_hi:[1,0]
	v_lshl_add_u64 v[82:83], s[14:15], 0, v[142:143]
	v_div_scale_f32 v141, s[44:45], v85, v85, v87
	v_rcp_f32_e32 v192, v141
	v_lshl_add_u64 v[82:83], v[98:99], 1, v[82:83]
	global_store_dwordx2 v[82:83], v[190:191], off offset:-1664
	v_fma_f32 v98, -v141, v192, 1.0
	v_fmac_f32_e32 v192, v98, v192
	v_div_scale_f32 v98, vcc, v87, v85, v87
	v_mul_f32_e32 v190, v98, v192
	v_fma_f32 v191, -v141, v190, v98
	v_fmac_f32_e32 v190, v191, v192
	v_fma_f32 v98, -v141, v190, v98
	v_div_scale_f32 v141, s[44:45], v84, v84, v86
	v_rcp_f32_e32 v193, v141
	v_div_fmas_f32 v98, v98, v192, v190
	v_mul_f32_e32 v190, 0xbfb8aa3b, v88
	v_mul_f32_e32 v191, 0xbfb8aa3b, v89
	v_div_fixup_f32 v85, v98, v85, v87
	v_fma_f32 v87, -v141, v193, 1.0
	v_exp_f32_e32 v190, v190
	v_exp_f32_e32 v191, v191
	v_fmac_f32_e32 v193, v87, v193
	v_div_scale_f32 v87, vcc, v86, v84, v86
	v_mul_f32_e32 v98, v87, v193
	v_fma_f32 v192, -v141, v98, v87
	v_fmac_f32_e32 v98, v192, v193
	v_pk_add_f32 v[190:191], v[190:191], 1.0 op_sel_hi:[1,0]
	v_fma_f32 v87, -v141, v98, v87
	v_div_scale_f32 v141, s[44:45], v191, v191, v89
	v_rcp_f32_e32 v192, v141
	v_div_fmas_f32 v87, v87, v193, v98
	v_div_fixup_f32 v84, v87, v84, v86
	v_cvt_pk_bf16_f32 v84, v84, v85
	v_fma_f32 v85, -v141, v192, 1.0
	v_fmac_f32_e32 v192, v85, v192
	v_div_scale_f32 v85, vcc, v89, v191, v89
	v_mul_f32_e32 v86, v85, v192
	v_fma_f32 v87, -v141, v86, v85
	v_fmac_f32_e32 v86, v87, v192
	v_div_scale_f32 v98, s[44:45], v190, v190, v88
	v_fma_f32 v85, -v141, v86, v85
	v_rcp_f32_e32 v141, v98
	v_div_fmas_f32 v85, v85, v192, v86
	v_div_fixup_f32 v85, v85, v191, v89
	v_div_scale_f32 v89, vcc, v88, v190, v88
	v_fma_f32 v86, -v98, v141, 1.0
	v_fmac_f32_e32 v141, v86, v141
	v_mul_f32_e32 v191, v89, v141
	v_fma_f32 v86, -v98, v191, v89
	v_fmac_f32_e32 v191, v86, v141
	v_mul_f32_e32 v86, 0xbfb8aa3b, v90
	v_mul_f32_e32 v87, 0xbfb8aa3b, v91
	v_exp_f32_e32 v86, v86
	v_exp_f32_e32 v87, v87
	v_fma_f32 v89, -v98, v191, v89
	v_div_fmas_f32 v89, v89, v141, v191
	v_div_fixup_f32 v88, v89, v190, v88
	v_pk_add_f32 v[86:87], v[86:87], 1.0 op_sel_hi:[1,0]
	v_cvt_pk_bf16_f32 v85, v88, v85
	v_div_scale_f32 v98, s[44:45], v87, v87, v91
	v_rcp_f32_e32 v141, v98
	global_store_dwordx2 v[82:83], v[84:85], off offset:-1648
	v_fma_f32 v84, -v98, v141, 1.0
	v_fmac_f32_e32 v141, v84, v141
	v_div_scale_f32 v84, vcc, v91, v87, v91
	v_mul_f32_e32 v85, v84, v141
	v_fma_f32 v88, -v98, v85, v84
	v_fmac_f32_e32 v85, v88, v141
	v_div_scale_f32 v88, s[44:45], v86, v86, v90
	v_rcp_f32_e32 v89, v88
	v_fma_f32 v84, -v98, v85, v84
	v_div_fmas_f32 v84, v84, v141, v85
	v_div_fixup_f32 v87, v84, v87, v91
	v_fma_f32 v84, -v88, v89, 1.0
	v_fmac_f32_e32 v89, v84, v89
	v_mul_f32_e32 v84, 0xbfb8aa3b, v92
	v_mul_f32_e32 v85, 0xbfb8aa3b, v93
	v_exp_f32_e32 v84, v84
	v_exp_f32_e32 v85, v85
	v_div_scale_f32 v91, vcc, v90, v86, v90
	v_mul_f32_e32 v98, v91, v89
	v_fma_f32 v141, -v88, v98, v91
	v_fmac_f32_e32 v98, v141, v89
	v_pk_add_f32 v[84:85], v[84:85], 1.0 op_sel_hi:[1,0]
	v_fma_f32 v88, -v88, v98, v91
	v_div_scale_f32 v91, s[44:45], v85, v85, v93
	v_rcp_f32_e32 v141, v91
	v_div_fmas_f32 v88, v88, v89, v98
	v_div_fixup_f32 v86, v88, v86, v90
	v_cvt_pk_bf16_f32 v86, v86, v87
	v_fma_f32 v87, -v91, v141, 1.0
	v_fmac_f32_e32 v141, v87, v141
	v_div_scale_f32 v87, vcc, v93, v85, v93
	v_mul_f32_e32 v88, v87, v141
	v_fma_f32 v89, -v91, v88, v87
	v_fmac_f32_e32 v88, v89, v141
	v_div_scale_f32 v90, s[44:45], v84, v84, v92
	v_fma_f32 v87, -v91, v88, v87
	v_rcp_f32_e32 v91, v90
	v_div_fmas_f32 v87, v87, v141, v88
	v_div_fixup_f32 v85, v87, v85, v93
	v_mul_f32_e32 v89, 0xbfb8aa3b, v95
	v_fma_f32 v87, -v90, v91, 1.0
	v_fmac_f32_e32 v91, v87, v91
	v_div_scale_f32 v87, vcc, v92, v84, v92
	v_mul_f32_e32 v93, v87, v91
	v_fma_f32 v88, -v90, v93, v87
	v_fmac_f32_e32 v93, v88, v91
	v_mul_f32_e32 v88, 0xbfb8aa3b, v94
	v_exp_f32_e32 v88, v88
	v_exp_f32_e32 v89, v89
	v_fma_f32 v87, -v90, v93, v87
	v_div_fmas_f32 v87, v87, v91, v93
	v_div_fixup_f32 v84, v87, v84, v92
	v_pk_add_f32 v[88:89], v[88:89], 1.0 op_sel_hi:[1,0]
	v_cvt_pk_bf16_f32 v87, v84, v85
	v_div_scale_f32 v90, s[44:45], v89, v89, v95
	v_rcp_f32_e32 v91, v90
	global_store_dwordx2 v[82:83], v[86:87], off offset:-1632
	v_fma_f32 v84, -v90, v91, 1.0
	v_fmac_f32_e32 v91, v84, v91
	v_div_scale_f32 v84, vcc, v95, v89, v95
	v_mul_f32_e32 v85, v84, v91
	v_fma_f32 v86, -v90, v85, v84
	v_fmac_f32_e32 v85, v86, v91
	v_div_scale_f32 v86, s[44:45], v88, v88, v94
	v_rcp_f32_e32 v87, v86
	v_fma_f32 v84, -v90, v85, v84
	v_div_fmas_f32 v84, v84, v91, v85
	v_div_fixup_f32 v89, v84, v89, v95
	v_fma_f32 v84, -v86, v87, 1.0
	v_fmac_f32_e32 v87, v84, v87
	v_mul_f32_e32 v84, 0xbfb8aa3b, v96
	v_mul_f32_e32 v85, 0xbfb8aa3b, v97
	v_exp_f32_e32 v84, v84
	v_exp_f32_e32 v85, v85
	v_div_scale_f32 v90, vcc, v94, v88, v94
	v_mul_f32_e32 v91, v90, v87
	v_fma_f32 v92, -v86, v91, v90
	v_fmac_f32_e32 v91, v92, v87
	v_pk_add_f32 v[84:85], v[84:85], 1.0 op_sel_hi:[1,0]
	v_fma_f32 v86, -v86, v91, v90
	v_div_scale_f32 v90, s[44:45], v85, v85, v97
	v_rcp_f32_e32 v92, v90
	v_div_fmas_f32 v86, v86, v87, v91
	v_div_fixup_f32 v86, v86, v88, v94
	v_cvt_pk_bf16_f32 v86, v86, v89
	v_fma_f32 v87, -v90, v92, 1.0
	v_fmac_f32_e32 v92, v87, v92
	v_div_scale_f32 v87, vcc, v97, v85, v97
	v_mul_f32_e32 v88, v87, v92
	v_fma_f32 v89, -v90, v88, v87
	v_fmac_f32_e32 v88, v89, v92
	v_div_scale_f32 v89, s[44:45], v84, v84, v96
	v_fma_f32 v87, -v90, v88, v87
	v_rcp_f32_e32 v90, v89
	v_div_fmas_f32 v87, v87, v92, v88
	v_div_fixup_f32 v85, v87, v85, v97
	v_fma_f32 v87, -v89, v90, 1.0
	v_fmac_f32_e32 v90, v87, v90
	v_div_scale_f32 v87, vcc, v96, v84, v96
	v_mul_f32_e32 v88, v87, v90
	v_fma_f32 v91, -v89, v88, v87
	v_fmac_f32_e32 v88, v91, v90
	v_fma_f32 v87, -v89, v88, v87
	v_div_fmas_f32 v87, v87, v90, v88
	v_div_fixup_f32 v84, v87, v84, v96
	v_cvt_pk_bf16_f32 v87, v84, v85
	global_store_dwordx2 v[82:83], v[86:87], off offset:-1616

.LBB0_778:
	s_load_dword s66, s[0:1], 0x468
	s_waitcnt lgkmcnt(0)
	s_cmpk_lg_u32 s66, 0x200
	s_cbranch_scc1 FUSE7_ORIG
	s_cmp_lt_i32 s23, 9
	s_cbranch_scc1 FUSE7_ORIG
	s_waitcnt vmcnt(0)
	s_barrier
	v_bfe_u32 v5, v0, 6, 2
	s_and_b32 s73, s2, 0x1ff
	s_nop 1
	v_readfirstlane_b32 s67, v5
	s_cmp_lg_u32 s67, 0
	s_cbranch_scc1 FUSE7_WAIT
	s_and_b32 s67, s73, 63
	s_lshl_b32 s68, s67, 6
	s_and_b32 s69, s67, 32
	s_lshl_b32 s69, s69, 6
	s_add_u32 s68, s68, s69
	s_add_u32 s68, s68, 0x1c00
	v_mov_b32_e32 v2, s68
	v_mov_b32_e32 v3, 1
	s_mov_b64 s[70:71], exec
	s_mov_b64 exec, 1
	s_mov_b32 s74, 0
	global_atomic_add v2, v3, s[20:21]
FUSE7_SPIN:
	global_load_dword v4, v2, s[20:21] sc1
	s_waitcnt vmcnt(0)
	v_readfirstlane_b32 s69, v4
	s_cmp_ge_u32 s69, 32
	s_cbranch_scc1 FUSE7_GOT
	s_add_i32 s74, s74, 1
	s_cmp_gt_u32 s74, 0x100000
	s_cbranch_scc1 FUSE7_GOT
	s_sleep 1
	s_branch FUSE7_SPIN
FUSE7_GOT:
	s_mov_b64 exec, s[70:71]
FUSE7_WAIT:
	s_barrier
	s_branch .LBB0_831
FUSE7_ORIG:
	s_cmp_lt_i32 s23, 9
	s_cbranch_scc1 .LBB0_831
	s_waitcnt vmcnt(0)
	s_waitcnt vmcnt(0)
	v_and_b32_e32 v3, 0x3ff, v0
	v_cmp_eq_u32_e32 vcc, 0, v3
	v_mov_b32_e32 v2, v146
	v_mov_b32_e32 v4, v148
	s_waitcnt lgkmcnt(0)
	s_barrier
	s_and_saveexec_b64 s[4:5], vcc
	s_cbranch_execz .LBB0_828
	v_cmp_eq_u32_e32 vcc, 0, v148
	v_mov_b32_e32 v2, v146
	v_mov_b32_e32 v4, v148
	s_waitcnt vmcnt(0) expcnt(0) lgkmcnt(0)
	s_and_saveexec_b64 s[6:7], vcc
	s_cbranch_execz .LBB0_795
	s_load_dwordx2 s[12:13], s[0:1], 0x468
	s_load_dword s3, s[0:1], 0x470
	s_add_u32 s8, s20, 0x1000
	s_addc_u32 s9, s21, 0
	s_add_u32 s10, s20, 0x1100
	s_waitcnt lgkmcnt(0)
	s_mul_i32 s11, s13, s12
	s_mul_i32 s3, s11, s3
	s_addc_u32 s11, s21, 0
	s_add_u32 s12, s20, 0x1200
	s_addc_u32 s13, s21, 0
	s_add_u32 s14, s20, 0x1300
	s_addc_u32 s15, s21, 0
	s_mov_b32 s26, 1
	v_mov_b32_e32 v19, 0
	s_branch .LBB0_783

.LBB0_831:
	s_cmp_gt_i32 s22, 8
	s_cselect_b64 s[4:5], -1, 0
	s_cmp_lt_i32 s23, 9
	s_cselect_b64 s[6:7], -1, 0
	s_or_b64 s[4:5], s[4:5], s[6:7]
	s_and_b64 vcc, exec, s[4:5]
	s_cbranch_vccnz .LBB0_896
	s_waitcnt vmcnt(0)
	s_load_dword s66, s[0:1], 0x468
	s_mov_b32 s75, s2
	s_movk_i32 s76, 0x3400
	s_mov_b32 s78, 0
	s_waitcnt lgkmcnt(0)
	s_mov_b32 s77, s66
	s_cmpk_lg_u32 s66, 0x200
	s_cbranch_scc1 P8_NORMP
	s_and_b32 s67, s2, 63
	s_lshr_b32 s68, s2, 6
	s_mul_i32 s75, s67, 48
	s_mul_i32 s68, s68, 6
	s_add_i32 s75, s75, s68
	s_lshl_b32 s76, s75, 2
	s_add_i32 s76, s76, 24
	s_mov_b32 s77, 1
	s_mov_b32 s78, 1
P8_NORMP:
	v_lshl_or_b32 v6, s75, 2, v1
	s_waitcnt lgkmcnt(0)
	s_mov_b32 s3, s76
	v_and_b32_e32 v29, 0x3ff, v0
	v_cmp_gt_i32_e32 vcc, s3, v6
	s_and_saveexec_b64 s[4:5], vcc
	s_cbranch_execz .LBB0_843
	s_load_dwordx4 s[16:19], s[0:1], 0x68
	s_load_dwordx4 s[8:11], s[0:1], 0x10
	s_load_dwordx2 s[6:7], s[0:1], 0x140
	s_load_dwordx4 s[12:15], s[0:1], 0x130
	v_and_b32_e32 v7, 63, v29
	v_mov_b32_e32 v9, 0
	v_lshlrev_b32_e32 v4, 4, v7
	v_mov_b32_e32 v5, v9
	v_lshlrev_b32_e32 v16, 1, v7
	v_mov_b32_e32 v17, v9
	s_waitcnt lgkmcnt(0)
	v_lshl_add_u64 v[10:11], s[8:9], 0, v[4:5]
	v_lshl_add_u64 v[16:17], s[6:7], 0, v[16:17]
	s_load_dwordx2 s[6:7], s[0:1], 0x120
	s_load_dwordx2 s[8:9], s[0:1], 0x80
	v_lshlrev_b32_e32 v2, 2, v7
	v_mov_b32_e32 v3, v9
	v_lshl_add_u64 v[14:15], s[10:11], 0, v[2:3]
	v_lshlrev_b32_e32 v26, 2, v2
	v_mbcnt_lo_u32_b32 v2, -1, 0
	v_mbcnt_hi_u32_b32 v34, -1, v2
	v_lshlrev_b32_e32 v8, 3, v7
	v_lshlrev_b32_e32 v18, 5, v7
	v_mov_b32_e32 v19, v9
	v_lshl_add_u64 v[20:21], s[12:13], 0, v[4:5]
	v_lshl_add_u64 v[22:23], s[18:19], 0, v[4:5]
	s_waitcnt lgkmcnt(0)
	v_lshl_add_u64 v[4:5], s[8:9], 0, v[4:5]
	s_mov_b64 s[8:9], 0x3000000
	s_mov_b32 s10, 0x3b800000
	v_and_b32_e32 v2, 64, v34
	s_lshl_b32 s3, s77, 2
	v_lshl_add_u64 v[12:13], s[14:15], 0, v[8:9]
	v_lshl_add_u64 v[18:19], s[16:17], 0, v[18:19]
	v_lshl_add_u64 v[24:25], v[4:5], 0, s[8:9]
	s_mov_b64 s[8:9], 0
	s_movk_i32 s16, 0x2fff
	s_movk_i32 s17, 0xff
	s_movk_i32 s18, 0xc00
	v_lshlrev_b32_e32 v8, 2, v8
	s_mov_b32 s11, 0x3b000000
	s_mov_b32 s19, 0x800000
	s_movk_i32 s24, 0xfff
	s_movk_i32 s25, 0x1100
	s_add_i32 s26, s76, -1
	v_add_u32_e32 v35, 64, v2
	v_xor_b32_e32 v36, 32, v34
	v_xor_b32_e32 v37, 16, v34
	v_xor_b32_e32 v38, 8, v34
	v_xor_b32_e32 v39, 4, v34
	v_xor_b32_e32 v40, 2, v34
	v_xor_b32_e32 v41, 1, v34
	v_mov_b32_e32 v28, 0x358637bd
	s_branch .LBB0_836

.LBB0_843:
	s_or_b64 exec, exec, s[4:5]
	s_cmp_eq_u32 s78, 1
	s_cbranch_scc0 P8_DONE
	s_mov_b32 s78, 2
	s_bitcmp1_b32 s2, 0
	s_cbranch_scc1 P8_DONE
	s_lshr_b32 s75, s2, 1
	s_add_u32 s75, s75, 0xc00
	s_lshl_b32 s76, s75, 2
	s_add_u32 s76, s76, 4
	s_branch P8_NORMP
P8_DONE:
	s_cmp_lt_i32 s23, 10
	s_cbranch_scc1 .LBB0_896
	s_waitcnt vmcnt(0)
	v_cmp_eq_u32_e32 vcc, 0, v29
	v_mov_b32_e32 v2, v146
	v_mov_b32_e32 v4, v148
	s_barrier
	s_and_saveexec_b64 s[4:5], vcc
	s_cbranch_execz .LBB0_893
	v_cmp_eq_u32_e32 vcc, 0, v148
	v_mov_b32_e32 v2, v146
	v_mov_b32_e32 v4, v148
	s_waitcnt vmcnt(0) expcnt(0) lgkmcnt(0)
	s_and_saveexec_b64 s[6:7], vcc
	s_cbranch_execz .LBB0_860
	s_load_dwordx2 s[12:13], s[0:1], 0x468
	s_load_dword s3, s[0:1], 0x470
	s_add_u32 s8, s20, 0x1000
	s_addc_u32 s9, s21, 0
	s_add_u32 s10, s20, 0x1100
	s_waitcnt lgkmcnt(0)
	s_mul_i32 s11, s13, s12
	s_mul_i32 s3, s11, s3
	s_addc_u32 s11, s21, 0
	s_add_u32 s12, s20, 0x1200
	s_addc_u32 s13, s21, 0
	s_add_u32 s14, s20, 0x1300
	s_addc_u32 s15, s21, 0
	s_mov_b32 s26, 1
	v_mov_b32_e32 v18, 0
	s_branch .LBB0_848

FUSE11_SPIN:
	global_load_dword v4, v2, s[20:21] sc1
	s_waitcnt vmcnt(0)
	v_readfirstlane_b32 s69, v4
	s_cmp_ge_u32 s69, 40
	s_cbranch_scc1 FUSE11_GOT
	s_add_i32 s74, s74, 1
	s_cmp_gt_u32 s74, 0x100000
	s_cbranch_scc1 FUSE11_GOT
	s_sleep 1
	s_branch FUSE11_SPIN

FUSE15_SPIN:
	global_load_dword v4, v2, s[20:21] sc1
	s_waitcnt vmcnt(0)
	v_readfirstlane_b32 s69, v4
	s_cmp_ge_u32 s69, 48
	s_cbranch_scc1 FUSE15_GOT
	s_add_i32 s74, s74, 1
	s_cmp_gt_u32 s74, 0x100000
	s_cbranch_scc1 FUSE15_GOT
	s_sleep 1
	s_branch FUSE15_SPIN

FUSE16_SPIN:
	global_load_dword v4, v2, s[20:21] sc1
	s_waitcnt vmcnt(0)
	v_readfirstlane_b32 s69, v4
	s_cmp_ge_u32 s69, 56
	s_cbranch_scc1 FUSE16_GOT
	s_add_i32 s74, s74, 1
	s_cmp_gt_u32 s74, 0x100000
	s_cbranch_scc1 FUSE16_GOT
	s_sleep 1
	s_branch FUSE16_SPIN

G1E_ph17_ST:
	v_and_b32_e32 v223, 31, v0
	v_mul_u32_u24_e32 v220, 0x110, v223
	v_bfe_u32 v223, v0, 5, 1
	v_lshl_add_u32 v220, v223, 4, v220
	v_bfe_u32 v224, v0, 6, 2
	v_mul_u32_u24_e32 v223, 0x2200, v224
	v_add_u32_e32 v220, v220, v223
	v_bfe_u32 v222, v0, 4, 2
	v_mul_u32_u24_e32 v221, 0x110, v222
	v_add_u32_e32 v221, v221, v223
	v_and_b32_e32 v223, 15, v0
	v_lshl_add_u32 v221, v223, 4, v221
	s_lshr_b32 s85, s35, 6
	s_and_b32 s85, s85, 7
	s_lshl_b32 s85, s85, 8
	s_and_b32 s84, s35, 63
	s_mulk_i32 s84, 0xc0
	v_lshrrev_b32_e32 v224, 1, v224
	v_mul_u32_u24_e32 v224, 0x60, v224
	v_add3_u32 v222, v222, v224, s84
	v_lshlrev_b32_e32 v222, 11, v222
	v_lshl_add_u32 v222, v223, 3, v222
	v_bfe_u32 v223, v0, 6, 1
	v_lshl_add_u32 v222, v223, 7, v222
	v_add_u32_e32 v222, s85, v222
	ds_write_b128 v220, v[82:85]
	ds_write_b128 v220, v[86:89] offset:32
	ds_write_b128 v220, v[90:93] offset:64
	ds_write_b128 v220, v[94:97] offset:96
	ds_write_b128 v220, v[66:69] offset:128
	ds_write_b128 v220, v[70:73] offset:160
	ds_write_b128 v220, v[74:77] offset:192
	ds_write_b128 v220, v[78:81] offset:224
	v_mov_b32_e32 v230, v222
	v_add_u32_e32 v231, 0x2000, v222
	v_add_u32_e32 v232, 0x4000, v222
	v_add_u32_e32 v233, 0x6000, v222
	v_add_u32_e32 v234, 0x8000, v222
	v_add_u32_e32 v235, 0xa000, v222
	v_add_u32_e32 v236, 0xc000, v222
	v_add_u32_e32 v237, 0xe000, v222
	s_waitcnt lgkmcnt(0)
	ds_read_b128 v[82:85], v221
	ds_read_b128 v[86:89], v221 offset:1088
	ds_read_b128 v[90:93], v221 offset:2176
	ds_read_b128 v[94:97], v221 offset:3264
	ds_read_b128 v[66:69], v221 offset:4352
	ds_read_b128 v[70:73], v221 offset:5440
	ds_read_b128 v[74:77], v221 offset:6528
	ds_read_b128 v[78:81], v221 offset:7616
	s_waitcnt lgkmcnt(7)
	v_cvt_pk_bf16_f32 v82, v82, v83
	v_cvt_pk_bf16_f32 v83, v84, v85
	global_store_dwordx2 v230, v[82:83], s[82:83] sc1
	s_waitcnt lgkmcnt(6)
	v_cvt_pk_bf16_f32 v86, v86, v87
	v_cvt_pk_bf16_f32 v87, v88, v89
	global_store_dwordx2 v231, v[86:87], s[82:83] sc1
	s_waitcnt lgkmcnt(5)
	v_cvt_pk_bf16_f32 v90, v90, v91
	v_cvt_pk_bf16_f32 v91, v92, v93
	global_store_dwordx2 v232, v[90:91], s[82:83] sc1
	s_waitcnt lgkmcnt(4)
	v_cvt_pk_bf16_f32 v94, v94, v95
	v_cvt_pk_bf16_f32 v95, v96, v97
	global_store_dwordx2 v233, v[94:95], s[82:83] sc1
	s_waitcnt lgkmcnt(3)
	v_cvt_pk_bf16_f32 v66, v66, v67
	v_cvt_pk_bf16_f32 v67, v68, v69
	global_store_dwordx2 v234, v[66:67], s[82:83] sc1
	s_waitcnt lgkmcnt(2)
	v_cvt_pk_bf16_f32 v70, v70, v71
	v_cvt_pk_bf16_f32 v71, v72, v73
	global_store_dwordx2 v235, v[70:71], s[82:83] sc1
	s_waitcnt lgkmcnt(1)
	v_cvt_pk_bf16_f32 v74, v74, v75
	v_cvt_pk_bf16_f32 v75, v76, v77
	global_store_dwordx2 v236, v[74:75], s[82:83] sc1
	s_waitcnt lgkmcnt(0)
	v_cvt_pk_bf16_f32 v78, v78, v79
	v_cvt_pk_bf16_f32 v79, v80, v81
	global_store_dwordx2 v237, v[78:79], s[82:83] sc1
	ds_write_b128 v220, v[50:53]
	ds_write_b128 v220, v[54:57] offset:32
	ds_write_b128 v220, v[58:61] offset:64
	ds_write_b128 v220, v[62:65] offset:96
	ds_write_b128 v220, v[34:37] offset:128
	ds_write_b128 v220, v[38:41] offset:160
	ds_write_b128 v220, v[42:45] offset:192
	ds_write_b128 v220, v[46:49] offset:224
	v_add_u32_e32 v230, 0x10000, v222
	v_add_u32_e32 v231, 0x12000, v222
	v_add_u32_e32 v232, 0x14000, v222
	v_add_u32_e32 v233, 0x16000, v222
	v_add_u32_e32 v234, 0x18000, v222
	v_add_u32_e32 v235, 0x1a000, v222
	v_add_u32_e32 v236, 0x1c000, v222
	v_add_u32_e32 v237, 0x1e000, v222
	s_waitcnt lgkmcnt(0)
	ds_read_b128 v[50:53], v221
	ds_read_b128 v[54:57], v221 offset:1088
	ds_read_b128 v[58:61], v221 offset:2176
	ds_read_b128 v[62:65], v221 offset:3264
	ds_read_b128 v[34:37], v221 offset:4352
	ds_read_b128 v[38:41], v221 offset:5440
	ds_read_b128 v[42:45], v221 offset:6528
	ds_read_b128 v[46:49], v221 offset:7616
	s_waitcnt lgkmcnt(7)
	v_cvt_pk_bf16_f32 v50, v50, v51
	v_cvt_pk_bf16_f32 v51, v52, v53
	global_store_dwordx2 v230, v[50:51], s[82:83] sc1
	s_waitcnt lgkmcnt(6)
	v_cvt_pk_bf16_f32 v54, v54, v55
	v_cvt_pk_bf16_f32 v55, v56, v57
	global_store_dwordx2 v231, v[54:55], s[82:83] sc1
	s_waitcnt lgkmcnt(5)
	v_cvt_pk_bf16_f32 v58, v58, v59
	v_cvt_pk_bf16_f32 v59, v60, v61
	global_store_dwordx2 v232, v[58:59], s[82:83] sc1
	s_waitcnt lgkmcnt(4)
	v_cvt_pk_bf16_f32 v62, v62, v63
	v_cvt_pk_bf16_f32 v63, v64, v65
	global_store_dwordx2 v233, v[62:63], s[82:83] sc1
	s_waitcnt lgkmcnt(3)
	v_cvt_pk_bf16_f32 v34, v34, v35
	v_cvt_pk_bf16_f32 v35, v36, v37
	global_store_dwordx2 v234, v[34:35], s[82:83] sc1
	s_waitcnt lgkmcnt(2)
	v_cvt_pk_bf16_f32 v38, v38, v39
	v_cvt_pk_bf16_f32 v39, v40, v41
	global_store_dwordx2 v235, v[38:39], s[82:83] sc1
	s_waitcnt lgkmcnt(1)
	v_cvt_pk_bf16_f32 v42, v42, v43
	v_cvt_pk_bf16_f32 v43, v44, v45
	global_store_dwordx2 v236, v[42:43], s[82:83] sc1
	s_waitcnt lgkmcnt(0)
	v_cvt_pk_bf16_f32 v46, v46, v47
	v_cvt_pk_bf16_f32 v47, v48, v49
	global_store_dwordx2 v237, v[46:47], s[82:83] sc1
	ds_write_b128 v220, v[18:21]
	ds_write_b128 v220, v[22:25] offset:32
	ds_write_b128 v220, v[26:29] offset:64
	ds_write_b128 v220, v[30:33] offset:96
	ds_write_b128 v220, v[2:5] offset:128
	ds_write_b128 v220, v[6:9] offset:160
	ds_write_b128 v220, v[10:13] offset:192
	ds_write_b128 v220, v[14:17] offset:224
	v_add_u32_e32 v230, 0x20000, v222
	v_add_u32_e32 v231, 0x22000, v222
	v_add_u32_e32 v232, 0x24000, v222
	v_add_u32_e32 v233, 0x26000, v222
	v_add_u32_e32 v234, 0x28000, v222
	v_add_u32_e32 v235, 0x2a000, v222
	v_add_u32_e32 v236, 0x2c000, v222
	v_add_u32_e32 v237, 0x2e000, v222
	s_waitcnt lgkmcnt(0)
	ds_read_b128 v[18:21], v221
	ds_read_b128 v[22:25], v221 offset:1088
	ds_read_b128 v[26:29], v221 offset:2176
	ds_read_b128 v[30:33], v221 offset:3264
	ds_read_b128 v[2:5], v221 offset:4352
	ds_read_b128 v[6:9], v221 offset:5440
	ds_read_b128 v[10:13], v221 offset:6528
	ds_read_b128 v[14:17], v221 offset:7616
	s_waitcnt lgkmcnt(7)
	v_cvt_pk_bf16_f32 v18, v18, v19
	v_cvt_pk_bf16_f32 v19, v20, v21
	global_store_dwordx2 v230, v[18:19], s[82:83] sc1
	s_waitcnt lgkmcnt(6)
	v_cvt_pk_bf16_f32 v22, v22, v23
	v_cvt_pk_bf16_f32 v23, v24, v25
	global_store_dwordx2 v231, v[22:23], s[82:83] sc1
	s_waitcnt lgkmcnt(5)
	v_cvt_pk_bf16_f32 v26, v26, v27
	v_cvt_pk_bf16_f32 v27, v28, v29
	global_store_dwordx2 v232, v[26:27], s[82:83] sc1
	s_waitcnt lgkmcnt(4)
	v_cvt_pk_bf16_f32 v30, v30, v31
	v_cvt_pk_bf16_f32 v31, v32, v33
	global_store_dwordx2 v233, v[30:31], s[82:83] sc1
	s_waitcnt lgkmcnt(3)
	v_cvt_pk_bf16_f32 v2, v2, v3
	v_cvt_pk_bf16_f32 v3, v4, v5
	global_store_dwordx2 v234, v[2:3], s[82:83] sc1
	s_waitcnt lgkmcnt(2)
	v_cvt_pk_bf16_f32 v6, v6, v7
	v_cvt_pk_bf16_f32 v7, v8, v9
	global_store_dwordx2 v235, v[6:7], s[82:83] sc1
	s_waitcnt lgkmcnt(1)
	v_cvt_pk_bf16_f32 v10, v10, v11
	v_cvt_pk_bf16_f32 v11, v12, v13
	global_store_dwordx2 v236, v[10:11], s[82:83] sc1
	s_waitcnt lgkmcnt(0)
	v_cvt_pk_bf16_f32 v14, v14, v15
	v_cvt_pk_bf16_f32 v15, v16, v17
	global_store_dwordx2 v237, v[14:15], s[82:83] sc1
	s_barrier
	s_mov_b64 s[4:5], exec
	s_branch .LBB0_1991

FUSE17_SPIN:
	global_load_dword v4, v2, s[20:21] sc1
	global_load_dword v8, v6, s[20:21] sc1
	global_load_dword v9, v7, s[20:21] sc1
	s_waitcnt vmcnt(0)
	v_min_u32_e32 v4, v4, v8
	v_min_u32_e32 v4, v4, v9
	s_nop 1
	v_readfirstlane_b32 s69, v4
	s_cmp_ge_u32 s69, 64
	s_cbranch_scc1 FUSE17_GOT
	s_add_i32 s74, s74, 1
	s_cmp_gt_u32 s74, 0x100000
	s_cbranch_scc1 FUSE17_GOT
	s_sleep 1
	s_branch FUSE17_SPIN

FUSE18_SPIN:
	global_load_dword v4, v2, s[20:21] sc1
	s_waitcnt vmcnt(0)
	v_readfirstlane_b32 s69, v4
	s_cmp_ge_u32 s69, 72
	s_cbranch_scc1 FUSE18_GOT
	s_add_i32 s74, s74, 1
	s_cmp_gt_u32 s74, 0x100000
	s_cbranch_scc1 FUSE18_GOT
	s_sleep 1
	s_branch FUSE18_SPIN

FUSE20_SPIN:
	global_load_dword v4, v2, s[20:21] sc1
	s_waitcnt vmcnt(0)
	v_readfirstlane_b32 s69, v4
	s_cmp_ge_u32 s69, 80
	s_cbranch_scc1 FUSE20_GOT
	s_add_i32 s74, s74, 1
	s_cmp_gt_u32 s74, 0x100000
	s_cbranch_scc1 FUSE20_GOT
	s_sleep 1
	s_branch FUSE20_SPIN
